# four-group start stagger of the in-proj GEMM (bits 3-4 of block index, s_sleep 100 each) on top of the cache-policy version
# speedup vs baseline: 1.0482x; 1.0070x over previous
; __device__ __forceinline__ void transpose_item(const float* W, int ldw, int nblk, bf16* WT, int ldt, LAS float* scr, int item, int lane) {
;     ...
; #pragma unroll 8
;     for (int i = 0; i < 32; ++i) { const int kk = 2 * i + (lane >> 5); scr[kk * 33 + (lane & 31)] = W[(size_t)(k0 + kk) * ldw + n0 + (lane & 31)]; }
.LBB0_21:
	s_lshl_b32 s12, s0, 1
	s_lshl_b32 s13, s5, 1
	v_or_b32_e32 v4, s13, v30
	s_add_i32 s14, s12, 4
	s_add_i32 s15, s13, 4
	v_mov_b32_e32 v41, v5
	s_add_i32 s17, s13, 8
	v_lshlrev_b64 v[54:55], 12, v[4:5]
	v_or_b32_e32 v40, s14, v3
	v_or_b32_e32 v4, s15, v30
	v_mov_b32_e32 v39, v5
	v_or_b32_e32 v38, s12, v3
	s_add_i32 s19, s13, 12
	v_lshlrev_b64 v[40:41], 12, v[40:41]
	v_lshlrev_b64 v[56:57], 12, v[4:5]
	v_or_b32_e32 v4, s17, v30
	s_add_i32 s16, s12, 8
	s_add_i32 s18, s12, 12
	s_add_i32 s35, s13, 16
	v_lshlrev_b64 v[38:39], 12, v[38:39]
	v_lshl_add_u64 v[54:55], v[28:29], 0, v[54:55]
	v_lshl_add_u64 v[40:41], v[28:29], 0, v[40:41]
	v_lshlrev_b64 v[58:59], 12, v[4:5]
	v_or_b32_e32 v4, s19, v30
	v_mov_b32_e32 v43, v5
	v_mov_b32_e32 v45, v5
	s_add_i32 s41, s13, 20
	v_or_b32_e32 v42, s16, v3
	v_or_b32_e32 v44, s18, v3
	v_lshl_add_u64 v[38:39], v[28:29], 0, v[38:39]
	v_lshl_add_u64 v[56:57], v[28:29], 0, v[56:57]
	global_load_dword v37, v[54:55], off nt
	global_load_dword v70, v[38:39], off nt
	global_load_dword v71, v[56:57], off nt
	global_load_dword v72, v[40:41], off nt
	v_lshlrev_b64 v[40:41], 12, v[4:5]
	v_or_b32_e32 v4, s35, v30
	s_add_i32 s33, s12, 16
	s_add_i32 s40, s12, 20
	s_add_i32 s55, s13, 24
	v_lshlrev_b64 v[42:43], 12, v[42:43]
	v_lshlrev_b64 v[44:45], 12, v[44:45]
	v_lshl_add_u64 v[38:39], v[28:29], 0, v[58:59]
	v_lshl_add_u64 v[40:41], v[28:29], 0, v[40:41]
	v_lshlrev_b64 v[54:55], 12, v[4:5]
	v_or_b32_e32 v4, s41, v30
	v_mov_b32_e32 v47, v5
	v_mov_b32_e32 v49, v5
	s_add_i32 s54, s12, 24
	s_add_i32 s56, s12, 28
	s_add_i32 s57, s13, 28
	v_or_b32_e32 v46, s33, v3
	v_or_b32_e32 v48, s40, v3
	v_lshl_add_u64 v[42:43], v[28:29], 0, v[42:43]
	v_lshl_add_u64 v[44:45], v[28:29], 0, v[44:45]
	global_load_dword v73, v[38:39], off nt
	global_load_dword v74, v[42:43], off nt
	global_load_dword v75, v[40:41], off nt
	global_load_dword v76, v[44:45], off nt
	v_lshlrev_b64 v[40:41], 12, v[4:5]
	v_or_b32_e32 v4, s55, v30
	v_mov_b32_e32 v51, v5
	v_mov_b32_e32 v53, v5
	v_or_b32_e32 v50, s54, v3
	v_or_b32_e32 v52, s56, v3
	v_lshlrev_b64 v[46:47], 12, v[46:47]
	v_lshlrev_b64 v[48:49], 12, v[48:49]
	v_lshl_add_u64 v[38:39], v[28:29], 0, v[54:55]
	v_lshl_add_u64 v[40:41], v[28:29], 0, v[40:41]
	v_lshlrev_b64 v[42:43], 12, v[4:5]
	v_or_b32_e32 v4, s57, v30
	v_lshlrev_b64 v[50:51], 12, v[50:51]
	v_lshlrev_b64 v[52:53], 12, v[52:53]
	v_lshl_add_u64 v[46:47], v[28:29], 0, v[46:47]
	v_lshl_add_u64 v[48:49], v[28:29], 0, v[48:49]
	global_load_dword v77, v[38:39], off nt
	global_load_dword v78, v[46:47], off nt
	global_load_dword v79, v[40:41], off nt
	global_load_dword v80, v[48:49], off nt
	v_lshl_add_u64 v[38:39], v[28:29], 0, v[42:43]
	v_lshlrev_b64 v[40:41], 12, v[4:5]
	v_lshl_add_u64 v[50:51], v[28:29], 0, v[50:51]
	v_lshl_add_u64 v[52:53], v[28:29], 0, v[52:53]
	v_lshl_add_u64 v[40:41], v[28:29], 0, v[40:41]
	global_load_dword v4, v[38:39], off nt
	global_load_dword v81, v[50:51], off nt
	global_load_dword v82, v[40:41], off nt
	global_load_dword v83, v[52:53], off nt
	v_or_b32_e32 v40, s12, v1
	v_or_b32_e32 v38, s13, v2
	s_add_i32 s5, s5, 16
	s_add_i32 s0, s0, 16
	s_add_i32 s11, s11, -16
	v_mad_u64_u32 v[38:39], s[12:13], v38, s8, v[8:9]
	v_mad_u64_u32 v[40:41], s[12:13], v40, s8, v[8:9]
	v_or_b32_e32 v39, s14, v1
	v_or_b32_e32 v41, s15, v2
	v_or_b32_e32 v48, s16, v1
	v_or_b32_e32 v46, s17, v2
	v_or_b32_e32 v52, s18, v1
	v_or_b32_e32 v50, s19, v2
	v_or_b32_e32 v56, s33, v1
	v_or_b32_e32 v54, s35, v2
	v_or_b32_e32 v60, s40, v1
	v_or_b32_e32 v58, s41, v2
	v_or_b32_e32 v64, s54, v1
	v_or_b32_e32 v62, s55, v2
	v_or_b32_e32 v68, s56, v1
	v_or_b32_e32 v66, s57, v2
	s_cmp_lg_u32 s11, 0
	v_mad_u64_u32 v[42:43], s[12:13], v41, s8, v[8:9]
	v_mad_u64_u32 v[44:45], s[12:13], v39, s8, v[8:9]
	v_mad_u64_u32 v[46:47], s[12:13], v46, s8, v[8:9]
	v_mad_u64_u32 v[48:49], s[12:13], v48, s8, v[8:9]
	v_mad_u64_u32 v[50:51], s[12:13], v50, s8, v[8:9]
	v_mad_u64_u32 v[52:53], s[12:13], v52, s8, v[8:9]
	v_mad_u64_u32 v[54:55], s[12:13], v54, s8, v[8:9]
	v_mad_u64_u32 v[56:57], s[12:13], v56, s8, v[8:9]
	v_mad_u64_u32 v[58:59], s[12:13], v58, s8, v[8:9]
	v_mad_u64_u32 v[60:61], s[12:13], v60, s8, v[8:9]
	v_mad_u64_u32 v[62:63], s[12:13], v62, s8, v[8:9]
	v_mad_u64_u32 v[64:65], s[12:13], v64, s8, v[8:9]
	v_mad_u64_u32 v[66:67], s[12:13], v66, s8, v[8:9]
	v_mad_u64_u32 v[68:69], s[12:13], v68, s8, v[8:9]
	s_waitcnt vmcnt(15)
	ds_write_b32 v38, v37
	s_waitcnt vmcnt(14)
	ds_write_b32 v40, v70
	s_waitcnt vmcnt(13)
	ds_write_b32 v42, v71
	s_waitcnt vmcnt(12)
	ds_write_b32 v44, v72
	s_waitcnt vmcnt(11)
	ds_write_b32 v46, v73
	s_waitcnt vmcnt(10)
	ds_write_b32 v48, v74
	s_waitcnt vmcnt(9)
	ds_write_b32 v50, v75
	s_waitcnt vmcnt(8)
	ds_write_b32 v52, v76
	s_waitcnt vmcnt(7)
	ds_write_b32 v54, v77
	s_waitcnt vmcnt(6)
	ds_write_b32 v56, v78
	s_waitcnt vmcnt(5)
	ds_write_b32 v58, v79
	s_waitcnt vmcnt(4)
	ds_write_b32 v60, v80
	s_waitcnt vmcnt(3)
	ds_write_b32 v62, v4
	s_waitcnt vmcnt(2)
	ds_write_b32 v64, v81
	s_waitcnt vmcnt(1)
	ds_write_b32 v66, v82
	s_waitcnt vmcnt(0)
	ds_write_b32 v68, v83
	s_cbranch_scc1 .LBB0_21
; #define GAS __attribute__((address_space(1)))
; #define LAS __attribute__((address_space(3)))
; #define LDS_WAIT() asm volatile("s_waitcnt lgkmcnt(0)" ::: "memory")
; __device__ __forceinline__ unsigned pk2(float lo, float hi) { return pg8::cvt_pk_bf16_c(lo, hi); }
; __device__ __forceinline__ void transpose_item(const float* W, int ldw, int nblk, bf16* WT, int ldt, LAS float* scr, int item, int lane) {
;     ...
;     const int c = lane & 7;
; #pragma unroll
;     for (int j = 0; j < 4; ++j) { const int n = (lane >> 3) + 8 * j; const LAS float* s = scr + (8 * c) * 33 + n;
;         v4u o; o.x = pk2(s[0 * 33], s[1 * 33]); o.y = pk2(s[2 * 33], s[3 * 33]); o.z = pk2(s[4 * 33], s[5 * 33]); o.w = pk2(s[6 * 33], s[7 * 33]);
;         *(GAS v4u*)(WT + (size_t)(n0 + n) * ldt + k0 + 8 * c) = o; }
;     LDS_WAIT(); asm volatile("" ::: "memory");
	s_waitcnt lgkmcnt(0)
	ds_read2_b32 v[28:29], v32 offset0:33 offset1:41
	ds_read2_b32 v[42:43], v32 offset1:8
	ds_read2_b32 v[44:45], v32 offset0:66 offset1:74
	ds_read2_b32 v[46:47], v32 offset0:99 offset1:107
	ds_read2_b32 v[48:49], v32 offset0:132 offset1:140
	ds_read2_b32 v[50:51], v32 offset0:165 offset1:173
	ds_read2_b32 v[52:53], v32 offset0:198 offset1:206
	ds_read2_b32 v[54:55], v32 offset0:231 offset1:239
	s_lshl_b32 s0, s4, 1
	v_or_b32_e32 v3, s6, v31
	v_lshl_add_u64 v[56:57], v[10:11], 0, s[0:1]
	v_lshlrev_b32_e32 v4, 11, v3
	s_waitcnt lgkmcnt(6)
	v_cvt_pk_bf16_f32 v38, v42, v28
	s_waitcnt lgkmcnt(4)
	v_cvt_pk_bf16_f32 v39, v44, v46
	s_waitcnt lgkmcnt(2)
	v_cvt_pk_bf16_f32 v40, v48, v50
	s_waitcnt lgkmcnt(0)
	v_cvt_pk_bf16_f32 v41, v52, v54
	v_lshl_add_u64 v[58:59], v[56:57], 0, v[4:5]
	global_store_dwordx4 v[58:59], v[38:41], off sc0 sc1
	v_or_b32_e32 v3, s6, v33
	v_lshlrev_b32_e32 v4, 11, v3
	v_cvt_pk_bf16_f32 v38, v43, v29
	v_cvt_pk_bf16_f32 v39, v45, v47
	v_cvt_pk_bf16_f32 v40, v49, v51
	v_cvt_pk_bf16_f32 v41, v53, v55
	ds_read2_b32 v[42:43], v32 offset0:49 offset1:57
	ds_read2_b32 v[44:45], v32 offset0:16 offset1:24
	ds_read2_b32 v[46:47], v32 offset0:82 offset1:90
	ds_read2_b32 v[48:49], v32 offset0:115 offset1:123
	ds_read2_b32 v[50:51], v32 offset0:148 offset1:156
	ds_read2_b32 v[52:53], v32 offset0:181 offset1:189
	ds_read2_b32 v[54:55], v32 offset0:214 offset1:222
	ds_read2_b32 v[58:59], v32 offset0:247 offset1:255
	v_or_b32_e32 v3, s6, v35
	v_lshl_add_u64 v[28:29], v[56:57], 0, v[4:5]
	v_lshlrev_b32_e32 v4, 11, v3
	v_or_b32_e32 v3, s6, v36
	global_store_dwordx4 v[28:29], v[38:41], off sc0 sc1
	v_lshl_add_u64 v[28:29], v[56:57], 0, v[4:5]
	v_lshlrev_b32_e32 v4, 11, v3
	s_waitcnt lgkmcnt(6)
	v_cvt_pk_bf16_f32 v38, v44, v42
	s_waitcnt lgkmcnt(4)
	v_cvt_pk_bf16_f32 v39, v46, v48
	s_waitcnt lgkmcnt(2)
	v_cvt_pk_bf16_f32 v40, v50, v52
	s_waitcnt lgkmcnt(0)
	v_cvt_pk_bf16_f32 v41, v54, v58
	global_store_dwordx4 v[28:29], v[38:41], off sc0 sc1
	v_lshl_add_u64 v[28:29], v[56:57], 0, v[4:5]
	s_mov_b64 s[4:5], 0
	v_cvt_pk_bf16_f32 v38, v45, v43
	v_cvt_pk_bf16_f32 v39, v47, v49
	v_cvt_pk_bf16_f32 v40, v51, v53
	v_cvt_pk_bf16_f32 v41, v55, v59
	global_store_dwordx4 v[28:29], v[38:41], off sc0 sc1
	s_waitcnt lgkmcnt(0)

; __device__ __forceinline__ void transpose_item(const float* W, int ldw, int nblk, bf16* WT, int ldt, LAS float* scr, int item, int lane) {
;     ...
; #pragma unroll 8
;     for (int i = 0; i < 32; ++i) { const int kk = 2 * i + (lane >> 5); scr[kk * 33 + (lane & 31)] = W[(size_t)(k0 + kk) * ldw + n0 + (lane & 31)]; }
.LBB0_25:
	s_lshl_b32 s11, s0, 1
	s_lshl_b32 s12, s5, 1
	v_or_b32_e32 v4, s12, v30
	s_add_i32 s14, s11, 4
	s_add_i32 s15, s12, 4
	v_mov_b32_e32 v41, v5
	s_add_i32 s17, s12, 8
	v_lshlrev_b64 v[54:55], 12, v[4:5]
	v_or_b32_e32 v40, s14, v3
	v_or_b32_e32 v4, s15, v30
	v_mov_b32_e32 v39, v5
	v_or_b32_e32 v38, s11, v3
	s_add_i32 s19, s12, 12
	v_lshlrev_b64 v[40:41], 12, v[40:41]
	v_lshlrev_b64 v[56:57], 12, v[4:5]
	v_or_b32_e32 v4, s17, v30
	s_add_i32 s16, s11, 8
	s_add_i32 s18, s11, 12
	s_add_i32 s35, s12, 16
	v_lshlrev_b64 v[38:39], 12, v[38:39]
	v_lshl_add_u64 v[54:55], v[28:29], 0, v[54:55]
	v_lshl_add_u64 v[40:41], v[28:29], 0, v[40:41]
	v_lshlrev_b64 v[58:59], 12, v[4:5]
	v_or_b32_e32 v4, s19, v30
	v_mov_b32_e32 v43, v5
	v_mov_b32_e32 v45, v5
	s_add_i32 s41, s12, 20
	v_or_b32_e32 v42, s16, v3
	v_or_b32_e32 v44, s18, v3
	v_lshl_add_u64 v[38:39], v[28:29], 0, v[38:39]
	v_lshl_add_u64 v[56:57], v[28:29], 0, v[56:57]
	global_load_dword v37, v[54:55], off nt
	global_load_dword v70, v[38:39], off nt
	global_load_dword v71, v[56:57], off nt
	global_load_dword v72, v[40:41], off nt
	v_lshlrev_b64 v[40:41], 12, v[4:5]
	v_or_b32_e32 v4, s35, v30
	s_add_i32 s33, s11, 16
	s_add_i32 s40, s11, 20
	s_add_i32 s55, s12, 24
	v_lshlrev_b64 v[42:43], 12, v[42:43]
	v_lshlrev_b64 v[44:45], 12, v[44:45]
	v_lshl_add_u64 v[38:39], v[28:29], 0, v[58:59]
	v_lshl_add_u64 v[40:41], v[28:29], 0, v[40:41]
	v_lshlrev_b64 v[54:55], 12, v[4:5]
	v_or_b32_e32 v4, s41, v30
	v_mov_b32_e32 v47, v5
	v_mov_b32_e32 v49, v5
	s_add_i32 s54, s11, 24
	s_add_i32 s56, s11, 28
	s_add_i32 s57, s12, 28
	v_or_b32_e32 v46, s33, v3
	v_or_b32_e32 v48, s40, v3
	v_lshl_add_u64 v[42:43], v[28:29], 0, v[42:43]
	v_lshl_add_u64 v[44:45], v[28:29], 0, v[44:45]
	global_load_dword v73, v[38:39], off nt
	global_load_dword v74, v[42:43], off nt
	global_load_dword v75, v[40:41], off nt
	global_load_dword v76, v[44:45], off nt
	v_lshlrev_b64 v[40:41], 12, v[4:5]
	v_or_b32_e32 v4, s55, v30
	v_mov_b32_e32 v51, v5
	v_mov_b32_e32 v53, v5
	v_or_b32_e32 v50, s54, v3
	v_or_b32_e32 v52, s56, v3
	v_lshlrev_b64 v[46:47], 12, v[46:47]
	v_lshlrev_b64 v[48:49], 12, v[48:49]
	v_lshl_add_u64 v[38:39], v[28:29], 0, v[54:55]
	v_lshl_add_u64 v[40:41], v[28:29], 0, v[40:41]
	v_lshlrev_b64 v[42:43], 12, v[4:5]
	v_or_b32_e32 v4, s57, v30
	v_lshlrev_b64 v[50:51], 12, v[50:51]
	v_lshlrev_b64 v[52:53], 12, v[52:53]
	v_lshl_add_u64 v[46:47], v[28:29], 0, v[46:47]
	v_lshl_add_u64 v[48:49], v[28:29], 0, v[48:49]
	global_load_dword v77, v[38:39], off nt
	global_load_dword v78, v[46:47], off nt
	global_load_dword v79, v[40:41], off nt
	global_load_dword v80, v[48:49], off nt
	v_lshl_add_u64 v[38:39], v[28:29], 0, v[42:43]
	v_lshlrev_b64 v[40:41], 12, v[4:5]
	v_lshl_add_u64 v[50:51], v[28:29], 0, v[50:51]
	v_lshl_add_u64 v[52:53], v[28:29], 0, v[52:53]
	v_lshl_add_u64 v[40:41], v[28:29], 0, v[40:41]
	global_load_dword v4, v[38:39], off nt
	global_load_dword v81, v[50:51], off nt
	global_load_dword v82, v[40:41], off nt
	global_load_dword v83, v[52:53], off nt
	v_or_b32_e32 v40, s11, v1
	v_or_b32_e32 v38, s12, v2
	s_add_i32 s5, s5, 16
	s_add_i32 s0, s0, 16
	s_add_i32 s7, s7, -16
	v_mad_u64_u32 v[38:39], s[12:13], v38, s8, v[8:9]
	v_mad_u64_u32 v[40:41], s[12:13], v40, s8, v[8:9]
	v_or_b32_e32 v39, s14, v1
	v_or_b32_e32 v41, s15, v2
	v_or_b32_e32 v48, s16, v1
	v_or_b32_e32 v46, s17, v2
	v_or_b32_e32 v52, s18, v1
	v_or_b32_e32 v50, s19, v2
	v_or_b32_e32 v56, s33, v1
	v_or_b32_e32 v54, s35, v2
	v_or_b32_e32 v60, s40, v1
	v_or_b32_e32 v58, s41, v2
	v_or_b32_e32 v64, s54, v1
	v_or_b32_e32 v62, s55, v2
	v_or_b32_e32 v68, s56, v1
	v_or_b32_e32 v66, s57, v2
	s_cmp_lg_u32 s7, 0
	v_mad_u64_u32 v[42:43], s[12:13], v41, s8, v[8:9]
	v_mad_u64_u32 v[44:45], s[12:13], v39, s8, v[8:9]
	v_mad_u64_u32 v[46:47], s[12:13], v46, s8, v[8:9]
	v_mad_u64_u32 v[48:49], s[12:13], v48, s8, v[8:9]
	v_mad_u64_u32 v[50:51], s[12:13], v50, s8, v[8:9]
	v_mad_u64_u32 v[52:53], s[12:13], v52, s8, v[8:9]
	v_mad_u64_u32 v[54:55], s[12:13], v54, s8, v[8:9]
	v_mad_u64_u32 v[56:57], s[12:13], v56, s8, v[8:9]
	v_mad_u64_u32 v[58:59], s[12:13], v58, s8, v[8:9]
	v_mad_u64_u32 v[60:61], s[12:13], v60, s8, v[8:9]
	v_mad_u64_u32 v[62:63], s[12:13], v62, s8, v[8:9]
	v_mad_u64_u32 v[64:65], s[12:13], v64, s8, v[8:9]
	v_mad_u64_u32 v[66:67], s[12:13], v66, s8, v[8:9]
	v_mad_u64_u32 v[68:69], s[12:13], v68, s8, v[8:9]
	s_waitcnt vmcnt(15)
	ds_write_b32 v38, v37
	s_waitcnt vmcnt(14)
	ds_write_b32 v40, v70
	s_waitcnt vmcnt(13)
	ds_write_b32 v42, v71
	s_waitcnt vmcnt(12)
	ds_write_b32 v44, v72
	s_waitcnt vmcnt(11)
	ds_write_b32 v46, v73
	s_waitcnt vmcnt(10)
	ds_write_b32 v48, v74
	s_waitcnt vmcnt(9)
	ds_write_b32 v50, v75
	s_waitcnt vmcnt(8)
	ds_write_b32 v52, v76
	s_waitcnt vmcnt(7)
	ds_write_b32 v54, v77
	s_waitcnt vmcnt(6)
	ds_write_b32 v56, v78
	s_waitcnt vmcnt(5)
	ds_write_b32 v58, v79
	s_waitcnt vmcnt(4)
	ds_write_b32 v60, v80
	s_waitcnt vmcnt(3)
	ds_write_b32 v62, v4
	s_waitcnt vmcnt(2)
	ds_write_b32 v64, v81
	s_waitcnt vmcnt(1)
	ds_write_b32 v66, v82
	s_waitcnt vmcnt(0)
	ds_write_b32 v68, v83
	s_cbranch_scc1 .LBB0_25
; #define GAS __attribute__((address_space(1)))
; #define LAS __attribute__((address_space(3)))
; #define LDS_WAIT() asm volatile("s_waitcnt lgkmcnt(0)" ::: "memory")
; __device__ __forceinline__ unsigned pk2(float lo, float hi) { return pg8::cvt_pk_bf16_c(lo, hi); }
; __device__ __forceinline__ void transpose_item(const float* W, int ldw, int nblk, bf16* WT, int ldt, LAS float* scr, int item, int lane) {
;     ...
;     const int c = lane & 7;
; #pragma unroll
;     for (int j = 0; j < 4; ++j) { const int n = (lane >> 3) + 8 * j; const LAS float* s = scr + (8 * c) * 33 + n;
;         v4u o; o.x = pk2(s[0 * 33], s[1 * 33]); o.y = pk2(s[2 * 33], s[3 * 33]); o.z = pk2(s[4 * 33], s[5 * 33]); o.w = pk2(s[6 * 33], s[7 * 33]);
;         *(GAS v4u*)(WT + (size_t)(n0 + n) * ldt + k0 + 8 * c) = o; }
;     LDS_WAIT(); asm volatile("" ::: "memory");
	s_waitcnt lgkmcnt(0)
	ds_read2_b32 v[28:29], v32 offset0:33 offset1:41
	ds_read2_b32 v[42:43], v32 offset1:8
	ds_read2_b32 v[44:45], v32 offset0:66 offset1:74
	ds_read2_b32 v[46:47], v32 offset0:99 offset1:107
	ds_read2_b32 v[48:49], v32 offset0:132 offset1:140
	ds_read2_b32 v[50:51], v32 offset0:165 offset1:173
	ds_read2_b32 v[52:53], v32 offset0:198 offset1:206
	ds_read2_b32 v[54:55], v32 offset0:231 offset1:239
	s_lshl_b32 s0, s4, 1
	v_or_b32_e32 v3, s6, v31
	v_lshl_add_u64 v[56:57], v[14:15], 0, s[0:1]
	v_lshlrev_b32_e32 v4, 12, v3
	s_waitcnt lgkmcnt(6)
	v_cvt_pk_bf16_f32 v38, v42, v28
	s_waitcnt lgkmcnt(4)
	v_cvt_pk_bf16_f32 v39, v44, v46
	s_waitcnt lgkmcnt(2)
	v_cvt_pk_bf16_f32 v40, v48, v50
	s_waitcnt lgkmcnt(0)
	v_cvt_pk_bf16_f32 v41, v52, v54
	v_lshl_add_u64 v[58:59], v[56:57], 0, v[4:5]
	global_store_dwordx4 v[58:59], v[38:41], off sc0 sc1
	v_or_b32_e32 v3, s6, v33
	v_lshlrev_b32_e32 v4, 12, v3
	v_cvt_pk_bf16_f32 v38, v43, v29
	v_cvt_pk_bf16_f32 v39, v45, v47
	v_cvt_pk_bf16_f32 v40, v49, v51
	v_cvt_pk_bf16_f32 v41, v53, v55
	ds_read2_b32 v[42:43], v32 offset0:49 offset1:57
	ds_read2_b32 v[44:45], v32 offset0:16 offset1:24
	ds_read2_b32 v[46:47], v32 offset0:82 offset1:90
	ds_read2_b32 v[48:49], v32 offset0:115 offset1:123
	ds_read2_b32 v[50:51], v32 offset0:148 offset1:156
	ds_read2_b32 v[52:53], v32 offset0:181 offset1:189
	ds_read2_b32 v[54:55], v32 offset0:214 offset1:222
	ds_read2_b32 v[58:59], v32 offset0:247 offset1:255
	v_or_b32_e32 v3, s6, v35
	v_lshl_add_u64 v[28:29], v[56:57], 0, v[4:5]
	v_lshlrev_b32_e32 v4, 12, v3
	v_or_b32_e32 v3, s6, v36
	global_store_dwordx4 v[28:29], v[38:41], off sc0 sc1
	v_lshl_add_u64 v[28:29], v[56:57], 0, v[4:5]
	v_lshlrev_b32_e32 v4, 12, v3
	s_waitcnt lgkmcnt(6)
	v_cvt_pk_bf16_f32 v38, v44, v42
	s_waitcnt lgkmcnt(4)
	v_cvt_pk_bf16_f32 v39, v46, v48
	s_waitcnt lgkmcnt(2)
	v_cvt_pk_bf16_f32 v40, v50, v52
	s_waitcnt lgkmcnt(0)
	v_cvt_pk_bf16_f32 v41, v54, v58
	global_store_dwordx4 v[28:29], v[38:41], off sc0 sc1
	v_lshl_add_u64 v[28:29], v[56:57], 0, v[4:5]
	s_nop 0
	v_cvt_pk_bf16_f32 v38, v45, v43
	v_cvt_pk_bf16_f32 v39, v47, v49
	v_cvt_pk_bf16_f32 v40, v51, v53
	v_cvt_pk_bf16_f32 v41, v55, v59
	global_store_dwordx4 v[28:29], v[38:41], off sc0 sc1
	s_waitcnt lgkmcnt(0)

; __device__ __forceinline__ void transpose_item(const float* W, int ldw, int nblk, bf16* WT, int ldt, LAS float* scr, int item, int lane) {
;     ...
; #pragma unroll 8
;     for (int i = 0; i < 32; ++i) { const int kk = 2 * i + (lane >> 5); scr[kk * 33 + (lane & 31)] = W[(size_t)(k0 + kk) * ldw + n0 + (lane & 31)]; }
.LBB0_30:
	s_lshl_b32 s11, s6, 1
	s_lshl_b32 s12, s0, 1
	v_or_b32_e32 v4, s12, v30
	s_add_i32 s14, s11, 4
	s_add_i32 s15, s12, 4
	v_mov_b32_e32 v41, v5
	s_add_i32 s17, s12, 8
	v_lshlrev_b64 v[54:55], 12, v[4:5]
	v_or_b32_e32 v40, s14, v3
	v_or_b32_e32 v4, s15, v30
	v_mov_b32_e32 v39, v5
	v_or_b32_e32 v38, s11, v3
	s_add_i32 s19, s12, 12
	v_lshlrev_b64 v[40:41], 12, v[40:41]
	v_lshlrev_b64 v[56:57], 12, v[4:5]
	v_or_b32_e32 v4, s17, v30
	s_add_i32 s16, s11, 8
	s_add_i32 s18, s11, 12
	s_add_i32 s35, s12, 16
	v_lshlrev_b64 v[38:39], 12, v[38:39]
	v_lshl_add_u64 v[54:55], v[28:29], 0, v[54:55]
	v_lshl_add_u64 v[40:41], v[28:29], 0, v[40:41]
	v_lshlrev_b64 v[58:59], 12, v[4:5]
	v_or_b32_e32 v4, s19, v30
	v_mov_b32_e32 v43, v5
	v_mov_b32_e32 v45, v5
	s_add_i32 s41, s12, 20
	v_or_b32_e32 v42, s16, v3
	v_or_b32_e32 v44, s18, v3
	v_lshl_add_u64 v[38:39], v[28:29], 0, v[38:39]
	v_lshl_add_u64 v[56:57], v[28:29], 0, v[56:57]
	global_load_dword v37, v[54:55], off nt
	global_load_dword v70, v[38:39], off nt
	global_load_dword v71, v[56:57], off nt
	global_load_dword v72, v[40:41], off nt
	v_lshlrev_b64 v[40:41], 12, v[4:5]
	v_or_b32_e32 v4, s35, v30
	s_add_i32 s33, s11, 16
	s_add_i32 s40, s11, 20
	s_add_i32 s55, s12, 24
	v_lshlrev_b64 v[42:43], 12, v[42:43]
	v_lshlrev_b64 v[44:45], 12, v[44:45]
	v_lshl_add_u64 v[38:39], v[28:29], 0, v[58:59]
	v_lshl_add_u64 v[40:41], v[28:29], 0, v[40:41]
	v_lshlrev_b64 v[54:55], 12, v[4:5]
	v_or_b32_e32 v4, s41, v30
	v_mov_b32_e32 v47, v5
	v_mov_b32_e32 v49, v5
	s_add_i32 s54, s11, 24
	s_add_i32 s56, s11, 28
	s_add_i32 s57, s12, 28
	v_or_b32_e32 v46, s33, v3
	v_or_b32_e32 v48, s40, v3
	v_lshl_add_u64 v[42:43], v[28:29], 0, v[42:43]
	v_lshl_add_u64 v[44:45], v[28:29], 0, v[44:45]
	global_load_dword v73, v[38:39], off nt
	global_load_dword v74, v[42:43], off nt
	global_load_dword v75, v[40:41], off nt
	global_load_dword v76, v[44:45], off nt
	v_lshlrev_b64 v[40:41], 12, v[4:5]
	v_or_b32_e32 v4, s55, v30
	v_mov_b32_e32 v51, v5
	v_mov_b32_e32 v53, v5
	v_or_b32_e32 v50, s54, v3
	v_or_b32_e32 v52, s56, v3
	v_lshlrev_b64 v[46:47], 12, v[46:47]
	v_lshlrev_b64 v[48:49], 12, v[48:49]
	v_lshl_add_u64 v[38:39], v[28:29], 0, v[54:55]
	v_lshl_add_u64 v[40:41], v[28:29], 0, v[40:41]
	v_lshlrev_b64 v[42:43], 12, v[4:5]
	v_or_b32_e32 v4, s57, v30
	v_lshlrev_b64 v[50:51], 12, v[50:51]
	v_lshlrev_b64 v[52:53], 12, v[52:53]
	v_lshl_add_u64 v[46:47], v[28:29], 0, v[46:47]
	v_lshl_add_u64 v[48:49], v[28:29], 0, v[48:49]
	global_load_dword v77, v[38:39], off nt
	global_load_dword v78, v[46:47], off nt
	global_load_dword v79, v[40:41], off nt
	global_load_dword v80, v[48:49], off nt
	v_lshl_add_u64 v[38:39], v[28:29], 0, v[42:43]
	v_lshlrev_b64 v[40:41], 12, v[4:5]
	v_lshl_add_u64 v[50:51], v[28:29], 0, v[50:51]
	v_lshl_add_u64 v[52:53], v[28:29], 0, v[52:53]
	v_lshl_add_u64 v[40:41], v[28:29], 0, v[40:41]
	global_load_dword v4, v[38:39], off nt
	global_load_dword v81, v[50:51], off nt
	global_load_dword v82, v[40:41], off nt
	global_load_dword v83, v[52:53], off nt
	v_or_b32_e32 v40, s11, v1
	v_or_b32_e32 v38, s12, v2
	s_add_i32 s0, s0, 16
	s_add_i32 s6, s6, 16
	s_add_i32 s7, s7, -16
	v_mad_u64_u32 v[38:39], s[12:13], v38, s8, v[8:9]
	v_mad_u64_u32 v[40:41], s[12:13], v40, s8, v[8:9]
	v_or_b32_e32 v39, s14, v1
	v_or_b32_e32 v41, s15, v2
	v_or_b32_e32 v48, s16, v1
	v_or_b32_e32 v46, s17, v2
	v_or_b32_e32 v52, s18, v1
	v_or_b32_e32 v50, s19, v2
	v_or_b32_e32 v56, s33, v1
	v_or_b32_e32 v54, s35, v2
	v_or_b32_e32 v60, s40, v1
	v_or_b32_e32 v58, s41, v2
	v_or_b32_e32 v64, s54, v1
	v_or_b32_e32 v62, s55, v2
	v_or_b32_e32 v68, s56, v1
	v_or_b32_e32 v66, s57, v2
	s_cmp_lg_u32 s7, 0
	v_mad_u64_u32 v[42:43], s[12:13], v41, s8, v[8:9]
	v_mad_u64_u32 v[44:45], s[12:13], v39, s8, v[8:9]
	v_mad_u64_u32 v[46:47], s[12:13], v46, s8, v[8:9]
	v_mad_u64_u32 v[48:49], s[12:13], v48, s8, v[8:9]
	v_mad_u64_u32 v[50:51], s[12:13], v50, s8, v[8:9]
	v_mad_u64_u32 v[52:53], s[12:13], v52, s8, v[8:9]
	v_mad_u64_u32 v[54:55], s[12:13], v54, s8, v[8:9]
	v_mad_u64_u32 v[56:57], s[12:13], v56, s8, v[8:9]
	v_mad_u64_u32 v[58:59], s[12:13], v58, s8, v[8:9]
	v_mad_u64_u32 v[60:61], s[12:13], v60, s8, v[8:9]
	v_mad_u64_u32 v[62:63], s[12:13], v62, s8, v[8:9]
	v_mad_u64_u32 v[64:65], s[12:13], v64, s8, v[8:9]
	v_mad_u64_u32 v[66:67], s[12:13], v66, s8, v[8:9]
	v_mad_u64_u32 v[68:69], s[12:13], v68, s8, v[8:9]
	s_waitcnt vmcnt(15)
	ds_write_b32 v38, v37
	s_waitcnt vmcnt(14)
	ds_write_b32 v40, v70
	s_waitcnt vmcnt(13)
	ds_write_b32 v42, v71
	s_waitcnt vmcnt(12)
	ds_write_b32 v44, v72
	s_waitcnt vmcnt(11)
	ds_write_b32 v46, v73
	s_waitcnt vmcnt(10)
	ds_write_b32 v48, v74
	s_waitcnt vmcnt(9)
	ds_write_b32 v50, v75
	s_waitcnt vmcnt(8)
	ds_write_b32 v52, v76
	s_waitcnt vmcnt(7)
	ds_write_b32 v54, v77
	s_waitcnt vmcnt(6)
	ds_write_b32 v56, v78
	s_waitcnt vmcnt(5)
	ds_write_b32 v58, v79
	s_waitcnt vmcnt(4)
	ds_write_b32 v60, v80
	s_waitcnt vmcnt(3)
	ds_write_b32 v62, v4
	s_waitcnt vmcnt(2)
	ds_write_b32 v64, v81
	s_waitcnt vmcnt(1)
	ds_write_b32 v66, v82
	s_waitcnt vmcnt(0)
	ds_write_b32 v68, v83
	s_cbranch_scc1 .LBB0_30
; #define GAS __attribute__((address_space(1)))
; #define LAS __attribute__((address_space(3)))
; #define LDS_WAIT() asm volatile("s_waitcnt lgkmcnt(0)" ::: "memory")
; __device__ __forceinline__ unsigned pk2(float lo, float hi) { return pg8::cvt_pk_bf16_c(lo, hi); }
; __device__ __forceinline__ void transpose_item(const float* W, int ldw, int nblk, bf16* WT, int ldt, LAS float* scr, int item, int lane) {
;     ...
;     const int c = lane & 7;
; #pragma unroll
;     for (int j = 0; j < 4; ++j) { const int n = (lane >> 3) + 8 * j; const LAS float* s = scr + (8 * c) * 33 + n;
;         v4u o; o.x = pk2(s[0 * 33], s[1 * 33]); o.y = pk2(s[2 * 33], s[3 * 33]); o.z = pk2(s[4 * 33], s[5 * 33]); o.w = pk2(s[6 * 33], s[7 * 33]);
;         *(GAS v4u*)(WT + (size_t)(n0 + n) * ldt + k0 + 8 * c) = o; }
;     LDS_WAIT(); asm volatile("" ::: "memory");
	s_waitcnt lgkmcnt(0)
	ds_read2_b32 v[28:29], v32 offset0:33 offset1:41
	ds_read2_b32 v[42:43], v32 offset1:8
	ds_read2_b32 v[44:45], v32 offset0:66 offset1:74
	ds_read2_b32 v[46:47], v32 offset0:99 offset1:107
	ds_read2_b32 v[48:49], v32 offset0:132 offset1:140
	ds_read2_b32 v[50:51], v32 offset0:165 offset1:173
	ds_read2_b32 v[52:53], v32 offset0:198 offset1:206
	ds_read2_b32 v[54:55], v32 offset0:231 offset1:239
	s_lshl_b32 s0, s5, 1
	v_or_b32_e32 v3, s4, v31
	v_lshl_add_u64 v[56:57], v[18:19], 0, s[0:1]
	v_lshlrev_b32_e32 v4, 12, v3
	s_waitcnt lgkmcnt(6)
	v_cvt_pk_bf16_f32 v38, v42, v28
	s_waitcnt lgkmcnt(4)
	v_cvt_pk_bf16_f32 v39, v44, v46
	s_waitcnt lgkmcnt(2)
	v_cvt_pk_bf16_f32 v40, v48, v50
	s_waitcnt lgkmcnt(0)
	v_cvt_pk_bf16_f32 v41, v52, v54
	v_lshl_add_u64 v[58:59], v[56:57], 0, v[4:5]
	global_store_dwordx4 v[58:59], v[38:41], off sc0 sc1
	v_or_b32_e32 v3, s4, v33
	v_lshlrev_b32_e32 v4, 12, v3
	v_cvt_pk_bf16_f32 v38, v43, v29
	v_cvt_pk_bf16_f32 v39, v45, v47
	v_cvt_pk_bf16_f32 v40, v49, v51
	v_cvt_pk_bf16_f32 v41, v53, v55
	ds_read2_b32 v[42:43], v32 offset0:49 offset1:57
	ds_read2_b32 v[44:45], v32 offset0:16 offset1:24
	ds_read2_b32 v[46:47], v32 offset0:82 offset1:90
	ds_read2_b32 v[48:49], v32 offset0:115 offset1:123
	ds_read2_b32 v[50:51], v32 offset0:148 offset1:156
	ds_read2_b32 v[52:53], v32 offset0:181 offset1:189
	ds_read2_b32 v[54:55], v32 offset0:214 offset1:222
	ds_read2_b32 v[58:59], v32 offset0:247 offset1:255
	v_or_b32_e32 v3, s4, v35
	v_lshl_add_u64 v[28:29], v[56:57], 0, v[4:5]
	v_lshlrev_b32_e32 v4, 12, v3
	v_or_b32_e32 v3, s4, v36
	global_store_dwordx4 v[28:29], v[38:41], off sc0 sc1
	v_lshl_add_u64 v[28:29], v[56:57], 0, v[4:5]
	v_lshlrev_b32_e32 v4, 12, v3
	s_waitcnt lgkmcnt(6)
	v_cvt_pk_bf16_f32 v38, v44, v42
	s_waitcnt lgkmcnt(4)
	v_cvt_pk_bf16_f32 v39, v46, v48
	s_waitcnt lgkmcnt(2)
	v_cvt_pk_bf16_f32 v40, v50, v52
	s_waitcnt lgkmcnt(0)
	v_cvt_pk_bf16_f32 v41, v54, v58
	global_store_dwordx4 v[28:29], v[38:41], off sc0 sc1
	v_lshl_add_u64 v[28:29], v[56:57], 0, v[4:5]
	s_nop 0
	v_cvt_pk_bf16_f32 v38, v45, v43
	v_cvt_pk_bf16_f32 v39, v47, v49
	v_cvt_pk_bf16_f32 v40, v51, v53
	v_cvt_pk_bf16_f32 v41, v55, v59
	global_store_dwordx4 v[28:29], v[38:41], off sc0 sc1
	s_waitcnt lgkmcnt(0)

; #define GAS __attribute__((address_space(1)))
; #define LAS __attribute__((address_space(3)))
; #define LDS_WAIT() asm volatile("s_waitcnt lgkmcnt(0)" ::: "memory")
; __device__ __forceinline__ unsigned pk2(float lo, float hi) { return pg8::cvt_pk_bf16_c(lo, hi); }
; __device__ __forceinline__ void transpose_item(const float* W, int ldw, int nblk, bf16* WT, int ldt, LAS float* scr, int item, int lane) {
;     ...
; #pragma unroll 8
;     for (int i = 0; i < 32; ++i) { const int kk = 2 * i + (lane >> 5); scr[kk * 33 + (lane & 31)] = W[(size_t)(k0 + kk) * ldw + n0 + (lane & 31)]; }
;     LDS_WAIT(); asm volatile("" ::: "memory");
;     const int c = lane & 7;
; #pragma unroll
;     for (int j = 0; j < 4; ++j) { const int n = (lane >> 3) + 8 * j; const LAS float* s = scr + (8 * c) * 33 + n;
;         v4u o; o.x = pk2(s[0 * 33], s[1 * 33]); o.y = pk2(s[2 * 33], s[3 * 33]); o.z = pk2(s[4 * 33], s[5 * 33]); o.w = pk2(s[6 * 33], s[7 * 33]);
;         *(GAS v4u*)(WT + (size_t)(n0 + n) * ldt + k0 + 8 * c) = o; }
;     LDS_WAIT(); asm volatile("" ::: "memory");
.LBB0_35:
	s_lshl_b32 s11, s0, 1
	s_lshl_b32 s14, s6, 1
	v_or_b32_e32 v30, s11, v3
	v_or_b32_e32 v37, s14, v4
	s_add_i32 s15, s11, 4
	s_add_i32 s16, s14, 4
	s_add_i32 s17, s11, 8
	s_add_i32 s18, s14, 8
	s_add_i32 s19, s11, 12
	s_add_i32 s33, s14, 12
	s_add_i32 s35, s11, 16
	s_add_i32 s40, s14, 16
	s_add_i32 s41, s11, 20
	s_add_i32 s54, s14, 20
	s_add_i32 s55, s11, 24
	s_add_i32 s56, s14, 24
	s_add_i32 s57, s11, 28
	s_add_i32 s58, s14, 28
	v_mad_u64_u32 v[38:39], s[12:13], v37, s9, v[28:29]
	v_mad_u64_u32 v[40:41], s[12:13], v30, s9, v[28:29]
	v_or_b32_e32 v30, s15, v3
	v_or_b32_e32 v37, s16, v4
	v_or_b32_e32 v48, s17, v3
	v_or_b32_e32 v46, s18, v4
	v_or_b32_e32 v52, s19, v3
	v_or_b32_e32 v50, s33, v4
	v_or_b32_e32 v56, s35, v3
	v_or_b32_e32 v54, s40, v4
	v_or_b32_e32 v60, s41, v3
	v_or_b32_e32 v58, s54, v4
	v_or_b32_e32 v64, s55, v3
	v_or_b32_e32 v62, s56, v4
	v_or_b32_e32 v68, s57, v3
	v_or_b32_e32 v66, s58, v4
	v_mad_u64_u32 v[42:43], s[12:13], v37, s9, v[28:29]
	v_mad_u64_u32 v[44:45], s[12:13], v30, s9, v[28:29]
	v_mad_u64_u32 v[46:47], s[12:13], v46, s9, v[28:29]
	v_mad_u64_u32 v[48:49], s[12:13], v48, s9, v[28:29]
	v_mad_u64_u32 v[50:51], s[12:13], v50, s9, v[28:29]
	v_mad_u64_u32 v[52:53], s[12:13], v52, s9, v[28:29]
	v_mad_u64_u32 v[54:55], s[12:13], v54, s9, v[28:29]
	v_mad_u64_u32 v[56:57], s[12:13], v56, s9, v[28:29]
	v_mad_u64_u32 v[58:59], s[12:13], v58, s9, v[28:29]
	v_mad_u64_u32 v[60:61], s[12:13], v60, s9, v[28:29]
	v_mad_u64_u32 v[62:63], s[12:13], v62, s9, v[28:29]
	v_mad_u64_u32 v[64:65], s[12:13], v64, s9, v[28:29]
	v_mad_u64_u32 v[66:67], s[12:13], v66, s9, v[28:29]
	v_mad_u64_u32 v[68:69], s[12:13], v68, s9, v[28:29]
	global_load_dword v30, v[38:39], off nt
	global_load_dword v37, v[40:41], off nt
	global_load_dword v70, v[42:43], off nt
	global_load_dword v71, v[44:45], off nt
	global_load_dword v72, v[46:47], off nt
	global_load_dword v73, v[48:49], off nt
	global_load_dword v74, v[50:51], off nt
	global_load_dword v75, v[52:53], off nt
	global_load_dword v76, v[54:55], off nt
	global_load_dword v77, v[56:57], off nt
	global_load_dword v78, v[58:59], off nt
	global_load_dword v79, v[60:61], off nt
	global_load_dword v80, v[62:63], off nt
	global_load_dword v81, v[64:65], off nt
	global_load_dword v82, v[66:67], off nt
	global_load_dword v83, v[68:69], off nt
	v_or_b32_e32 v40, s11, v1
	v_or_b32_e32 v38, s14, v2
	s_add_i32 s6, s6, 16
	s_add_i32 s0, s0, 16
	s_add_i32 s7, s7, -16
	v_mad_u64_u32 v[38:39], s[12:13], v38, s8, v[8:9]
	v_mad_u64_u32 v[40:41], s[12:13], v40, s8, v[8:9]
	v_or_b32_e32 v39, s15, v1
	v_or_b32_e32 v41, s16, v2
	v_or_b32_e32 v48, s17, v1
	v_or_b32_e32 v46, s18, v2
	v_or_b32_e32 v52, s19, v1
	v_or_b32_e32 v50, s33, v2
	v_or_b32_e32 v56, s35, v1
	v_or_b32_e32 v54, s40, v2
	v_or_b32_e32 v60, s41, v1
	v_or_b32_e32 v58, s54, v2
	v_or_b32_e32 v64, s55, v1
	v_or_b32_e32 v62, s56, v2
	v_or_b32_e32 v68, s57, v1
	v_or_b32_e32 v66, s58, v2
	s_cmp_lg_u32 s7, 0
	v_mad_u64_u32 v[42:43], s[12:13], v41, s8, v[8:9]
	v_mad_u64_u32 v[44:45], s[12:13], v39, s8, v[8:9]
	v_mad_u64_u32 v[46:47], s[12:13], v46, s8, v[8:9]
	v_mad_u64_u32 v[48:49], s[12:13], v48, s8, v[8:9]
	v_mad_u64_u32 v[50:51], s[12:13], v50, s8, v[8:9]
	v_mad_u64_u32 v[52:53], s[12:13], v52, s8, v[8:9]
	v_mad_u64_u32 v[54:55], s[12:13], v54, s8, v[8:9]
	v_mad_u64_u32 v[56:57], s[12:13], v56, s8, v[8:9]
	v_mad_u64_u32 v[58:59], s[12:13], v58, s8, v[8:9]
	v_mad_u64_u32 v[60:61], s[12:13], v60, s8, v[8:9]
	v_mad_u64_u32 v[62:63], s[12:13], v62, s8, v[8:9]
	v_mad_u64_u32 v[64:65], s[12:13], v64, s8, v[8:9]
	v_mad_u64_u32 v[66:67], s[12:13], v66, s8, v[8:9]
	v_mad_u64_u32 v[68:69], s[12:13], v68, s8, v[8:9]
	s_waitcnt vmcnt(15)
	ds_write_b32 v38, v30
	s_waitcnt vmcnt(14)
	ds_write_b32 v40, v37
	s_waitcnt vmcnt(13)
	ds_write_b32 v42, v70
	s_waitcnt vmcnt(12)
	ds_write_b32 v44, v71
	s_waitcnt vmcnt(11)
	ds_write_b32 v46, v72
	s_waitcnt vmcnt(10)
	ds_write_b32 v48, v73
	s_waitcnt vmcnt(9)
	ds_write_b32 v50, v74
	s_waitcnt vmcnt(8)
	ds_write_b32 v52, v75
	s_waitcnt vmcnt(7)
	ds_write_b32 v54, v76
	s_waitcnt vmcnt(6)
	ds_write_b32 v56, v77
	s_waitcnt vmcnt(5)
	ds_write_b32 v58, v78
	s_waitcnt vmcnt(4)
	ds_write_b32 v60, v79
	s_waitcnt vmcnt(3)
	ds_write_b32 v62, v80
	s_waitcnt vmcnt(2)
	ds_write_b32 v64, v81
	s_waitcnt vmcnt(1)
	ds_write_b32 v66, v82
	s_waitcnt vmcnt(0)
	ds_write_b32 v68, v83
	s_cbranch_scc1 .LBB0_35
	s_waitcnt lgkmcnt(0)
	ds_read2_b32 v[28:29], v32 offset0:33 offset1:41
	ds_read2_b32 v[42:43], v32 offset1:8
	ds_read2_b32 v[44:45], v32 offset0:66 offset1:74
	ds_read2_b32 v[46:47], v32 offset0:99 offset1:107
	ds_read2_b32 v[48:49], v32 offset0:132 offset1:140
	ds_read2_b32 v[50:51], v32 offset0:165 offset1:173
	ds_read2_b32 v[52:53], v32 offset0:198 offset1:206
	ds_read2_b32 v[54:55], v32 offset0:231 offset1:239
	s_lshl_b32 s0, s5, 1
	v_or_b32_e32 v3, s4, v31
	v_lshl_add_u64 v[56:57], v[24:25], 0, s[0:1]
	v_lshlrev_b32_e32 v4, 11, v3
	s_waitcnt lgkmcnt(6)
	v_cvt_pk_bf16_f32 v38, v42, v28
	s_waitcnt lgkmcnt(4)
	v_cvt_pk_bf16_f32 v39, v44, v46
	s_waitcnt lgkmcnt(2)
	v_cvt_pk_bf16_f32 v40, v48, v50
	s_waitcnt lgkmcnt(0)
	v_cvt_pk_bf16_f32 v41, v52, v54
	v_lshl_add_u64 v[58:59], v[56:57], 0, v[4:5]
	global_store_dwordx4 v[58:59], v[38:41], off sc0 sc1
	v_or_b32_e32 v3, s4, v33
	v_lshlrev_b32_e32 v4, 11, v3
	v_cvt_pk_bf16_f32 v38, v43, v29
	v_cvt_pk_bf16_f32 v39, v45, v47
	v_cvt_pk_bf16_f32 v40, v49, v51
	v_cvt_pk_bf16_f32 v41, v53, v55
	ds_read2_b32 v[42:43], v32 offset0:49 offset1:57
	ds_read2_b32 v[44:45], v32 offset0:16 offset1:24
	ds_read2_b32 v[46:47], v32 offset0:82 offset1:90
	ds_read2_b32 v[48:49], v32 offset0:115 offset1:123
	ds_read2_b32 v[50:51], v32 offset0:148 offset1:156
	ds_read2_b32 v[52:53], v32 offset0:181 offset1:189
	ds_read2_b32 v[54:55], v32 offset0:214 offset1:222
	ds_read2_b32 v[58:59], v32 offset0:247 offset1:255
	v_or_b32_e32 v3, s4, v35
	v_lshl_add_u64 v[28:29], v[56:57], 0, v[4:5]
	v_lshlrev_b32_e32 v4, 11, v3
	v_or_b32_e32 v3, s4, v36
	global_store_dwordx4 v[28:29], v[38:41], off sc0 sc1
	v_lshl_add_u64 v[28:29], v[56:57], 0, v[4:5]
	v_lshlrev_b32_e32 v4, 11, v3
	s_waitcnt lgkmcnt(6)
	v_cvt_pk_bf16_f32 v38, v44, v42
	s_waitcnt lgkmcnt(4)
	v_cvt_pk_bf16_f32 v39, v46, v48
	s_waitcnt lgkmcnt(2)
	v_cvt_pk_bf16_f32 v40, v50, v52
	s_waitcnt lgkmcnt(0)
	v_cvt_pk_bf16_f32 v41, v54, v58
	global_store_dwordx4 v[28:29], v[38:41], off sc0 sc1
	v_lshl_add_u64 v[28:29], v[56:57], 0, v[4:5]
	s_nop 0
	v_cvt_pk_bf16_f32 v38, v45, v43
	v_cvt_pk_bf16_f32 v39, v47, v49
	v_cvt_pk_bf16_f32 v40, v51, v53
	v_cvt_pk_bf16_f32 v41, v55, v59
	global_store_dwordx4 v[28:29], v[38:41], off sc0 sc1
	s_waitcnt lgkmcnt(0)

; #define GAS __attribute__((address_space(1)))
; #define LAS __attribute__((address_space(3)))
; #define LDS_WAIT() asm volatile("s_waitcnt lgkmcnt(0)" ::: "memory")
; __device__ __forceinline__ unsigned pk2(float lo, float hi) { return pg8::cvt_pk_bf16_c(lo, hi); }
; __device__ __forceinline__ void transpose_item(const float* W, int ldw, int nblk, bf16* WT, int ldt, LAS float* scr, int item, int lane) {
;     ...
; #pragma unroll 8
;     for (int i = 0; i < 32; ++i) { const int kk = 2 * i + (lane >> 5); scr[kk * 33 + (lane & 31)] = W[(size_t)(k0 + kk) * ldw + n0 + (lane & 31)]; }
;     LDS_WAIT(); asm volatile("" ::: "memory");
;     const int c = lane & 7;
; #pragma unroll
;     for (int j = 0; j < 4; ++j) { const int n = (lane >> 3) + 8 * j; const LAS float* s = scr + (8 * c) * 33 + n;
;         v4u o; o.x = pk2(s[0 * 33], s[1 * 33]); o.y = pk2(s[2 * 33], s[3 * 33]); o.z = pk2(s[4 * 33], s[5 * 33]); o.w = pk2(s[6 * 33], s[7 * 33]);
;         *(GAS v4u*)(WT + (size_t)(n0 + n) * ldt + k0 + 8 * c) = o; }
;     LDS_WAIT(); asm volatile("" ::: "memory");
.LBB0_39:
	s_lshl_b32 s11, s0, 1
	s_lshl_b32 s14, s5, 1
	v_or_b32_e32 v30, s11, v3
	v_or_b32_e32 v37, s14, v4
	s_add_i32 s15, s11, 4
	s_add_i32 s16, s14, 4
	s_add_i32 s17, s11, 8
	s_add_i32 s18, s14, 8
	s_add_i32 s19, s11, 12
	s_add_i32 s33, s14, 12
	s_add_i32 s35, s11, 16
	s_add_i32 s40, s14, 16
	s_add_i32 s41, s11, 20
	s_add_i32 s54, s14, 20
	s_add_i32 s55, s11, 24
	s_add_i32 s56, s14, 24
	s_add_i32 s57, s11, 28
	s_add_i32 s58, s14, 28
	v_mad_i64_i32 v[38:39], s[12:13], v37, s9, v[28:29]
	v_mad_i64_i32 v[40:41], s[12:13], v30, s9, v[28:29]
	v_or_b32_e32 v30, s15, v3
	v_or_b32_e32 v37, s16, v4
	v_or_b32_e32 v48, s17, v3
	v_or_b32_e32 v46, s18, v4
	v_or_b32_e32 v52, s19, v3
	v_or_b32_e32 v50, s33, v4
	v_or_b32_e32 v56, s35, v3
	v_or_b32_e32 v54, s40, v4
	v_or_b32_e32 v60, s41, v3
	v_or_b32_e32 v58, s54, v4
	v_or_b32_e32 v64, s55, v3
	v_or_b32_e32 v62, s56, v4
	v_or_b32_e32 v68, s57, v3
	v_or_b32_e32 v66, s58, v4
	v_mad_i64_i32 v[42:43], s[12:13], v37, s9, v[28:29]
	v_mad_i64_i32 v[44:45], s[12:13], v30, s9, v[28:29]
	v_mad_i64_i32 v[46:47], s[12:13], v46, s9, v[28:29]
	v_mad_i64_i32 v[48:49], s[12:13], v48, s9, v[28:29]
	v_mad_i64_i32 v[50:51], s[12:13], v50, s9, v[28:29]
	v_mad_i64_i32 v[52:53], s[12:13], v52, s9, v[28:29]
	v_mad_i64_i32 v[54:55], s[12:13], v54, s9, v[28:29]
	v_mad_i64_i32 v[56:57], s[12:13], v56, s9, v[28:29]
	v_mad_i64_i32 v[58:59], s[12:13], v58, s9, v[28:29]
	v_mad_i64_i32 v[60:61], s[12:13], v60, s9, v[28:29]
	v_mad_i64_i32 v[62:63], s[12:13], v62, s9, v[28:29]
	v_mad_i64_i32 v[64:65], s[12:13], v64, s9, v[28:29]
	v_mad_i64_i32 v[66:67], s[12:13], v66, s9, v[28:29]
	v_mad_i64_i32 v[68:69], s[12:13], v68, s9, v[28:29]
	global_load_dword v30, v[38:39], off nt
	global_load_dword v37, v[40:41], off nt
	global_load_dword v70, v[42:43], off nt
	global_load_dword v71, v[44:45], off nt
	global_load_dword v72, v[46:47], off nt
	global_load_dword v73, v[48:49], off nt
	global_load_dword v74, v[50:51], off nt
	global_load_dword v75, v[52:53], off nt
	global_load_dword v76, v[54:55], off nt
	global_load_dword v77, v[56:57], off nt
	global_load_dword v78, v[58:59], off nt
	global_load_dword v79, v[60:61], off nt
	global_load_dword v80, v[62:63], off nt
	global_load_dword v81, v[64:65], off nt
	global_load_dword v82, v[66:67], off nt
	global_load_dword v83, v[68:69], off nt
	v_or_b32_e32 v40, s11, v1
	v_or_b32_e32 v38, s14, v2
	s_add_i32 s5, s5, 16
	s_add_i32 s0, s0, 16
	s_add_i32 s7, s7, -16
	v_mad_u64_u32 v[38:39], s[12:13], v38, s8, v[8:9]
	v_mad_u64_u32 v[40:41], s[12:13], v40, s8, v[8:9]
	v_or_b32_e32 v39, s15, v1
	v_or_b32_e32 v41, s16, v2
	v_or_b32_e32 v48, s17, v1
	v_or_b32_e32 v46, s18, v2
	v_or_b32_e32 v52, s19, v1
	v_or_b32_e32 v50, s33, v2
	v_or_b32_e32 v56, s35, v1
	v_or_b32_e32 v54, s40, v2
	v_or_b32_e32 v60, s41, v1
	v_or_b32_e32 v58, s54, v2
	v_or_b32_e32 v64, s55, v1
	v_or_b32_e32 v62, s56, v2
	v_or_b32_e32 v68, s57, v1
	v_or_b32_e32 v66, s58, v2
	s_cmp_lg_u32 s7, 0
	v_mad_u64_u32 v[42:43], s[12:13], v41, s8, v[8:9]
	v_mad_u64_u32 v[44:45], s[12:13], v39, s8, v[8:9]
	v_mad_u64_u32 v[46:47], s[12:13], v46, s8, v[8:9]
	v_mad_u64_u32 v[48:49], s[12:13], v48, s8, v[8:9]
	v_mad_u64_u32 v[50:51], s[12:13], v50, s8, v[8:9]
	v_mad_u64_u32 v[52:53], s[12:13], v52, s8, v[8:9]
	v_mad_u64_u32 v[54:55], s[12:13], v54, s8, v[8:9]
	v_mad_u64_u32 v[56:57], s[12:13], v56, s8, v[8:9]
	v_mad_u64_u32 v[58:59], s[12:13], v58, s8, v[8:9]
	v_mad_u64_u32 v[60:61], s[12:13], v60, s8, v[8:9]
	v_mad_u64_u32 v[62:63], s[12:13], v62, s8, v[8:9]
	v_mad_u64_u32 v[64:65], s[12:13], v64, s8, v[8:9]
	v_mad_u64_u32 v[66:67], s[12:13], v66, s8, v[8:9]
	v_mad_u64_u32 v[68:69], s[12:13], v68, s8, v[8:9]
	s_waitcnt vmcnt(15)
	ds_write_b32 v38, v30
	s_waitcnt vmcnt(14)
	ds_write_b32 v40, v37
	s_waitcnt vmcnt(13)
	ds_write_b32 v42, v70
	s_waitcnt vmcnt(12)
	ds_write_b32 v44, v71
	s_waitcnt vmcnt(11)
	ds_write_b32 v46, v72
	s_waitcnt vmcnt(10)
	ds_write_b32 v48, v73
	s_waitcnt vmcnt(9)
	ds_write_b32 v50, v74
	s_waitcnt vmcnt(8)
	ds_write_b32 v52, v75
	s_waitcnt vmcnt(7)
	ds_write_b32 v54, v76
	s_waitcnt vmcnt(6)
	ds_write_b32 v56, v77
	s_waitcnt vmcnt(5)
	ds_write_b32 v58, v78
	s_waitcnt vmcnt(4)
	ds_write_b32 v60, v79
	s_waitcnt vmcnt(3)
	ds_write_b32 v62, v80
	s_waitcnt vmcnt(2)
	ds_write_b32 v64, v81
	s_waitcnt vmcnt(1)
	ds_write_b32 v66, v82
	s_waitcnt vmcnt(0)
	ds_write_b32 v68, v83
	s_cbranch_scc1 .LBB0_39
	s_waitcnt lgkmcnt(0)
	ds_read2_b32 v[28:29], v32 offset0:33 offset1:41
	ds_read2_b32 v[42:43], v32 offset1:8
	ds_read2_b32 v[44:45], v32 offset0:66 offset1:74
	ds_read2_b32 v[46:47], v32 offset0:99 offset1:107
	ds_read2_b32 v[48:49], v32 offset0:132 offset1:140
	ds_read2_b32 v[50:51], v32 offset0:165 offset1:173
	ds_read2_b32 v[52:53], v32 offset0:198 offset1:206
	ds_read2_b32 v[54:55], v32 offset0:231 offset1:239
	v_or_b32_e32 v58, s4, v31
	s_ashr_i32 s7, s6, 31
	v_ashrrev_i32_e32 v59, 31, v58
	v_lshl_add_u64 v[56:57], s[6:7], 1, v[26:27]
	v_lshlrev_b64 v[58:59], 11, v[58:59]
	s_waitcnt lgkmcnt(6)
	v_cvt_pk_bf16_f32 v38, v42, v28
	s_waitcnt lgkmcnt(4)
	v_cvt_pk_bf16_f32 v39, v44, v46
	s_waitcnt lgkmcnt(2)
	v_cvt_pk_bf16_f32 v40, v48, v50
	s_waitcnt lgkmcnt(0)
	v_cvt_pk_bf16_f32 v41, v52, v54
	v_lshl_add_u64 v[58:59], v[56:57], 0, v[58:59]
	v_or_b32_e32 v28, s4, v33
	global_store_dwordx4 v[58:59], v[38:41], off sc0 sc1
	s_nop 1
	v_cvt_pk_bf16_f32 v38, v43, v29
	v_ashrrev_i32_e32 v29, 31, v28
	v_cvt_pk_bf16_f32 v39, v45, v47
	v_cvt_pk_bf16_f32 v40, v49, v51
	v_cvt_pk_bf16_f32 v41, v53, v55
	v_lshlrev_b64 v[28:29], 11, v[28:29]
	ds_read2_b32 v[42:43], v32 offset0:49 offset1:57
	ds_read2_b32 v[44:45], v32 offset0:16 offset1:24
	ds_read2_b32 v[46:47], v32 offset0:82 offset1:90
	ds_read2_b32 v[48:49], v32 offset0:115 offset1:123
	ds_read2_b32 v[50:51], v32 offset0:148 offset1:156
	ds_read2_b32 v[52:53], v32 offset0:181 offset1:189
	ds_read2_b32 v[54:55], v32 offset0:214 offset1:222
	ds_read2_b32 v[58:59], v32 offset0:247 offset1:255
	v_lshl_add_u64 v[28:29], v[56:57], 0, v[28:29]
	global_store_dwordx4 v[28:29], v[38:41], off sc0 sc1
	v_or_b32_e32 v28, s4, v35
	v_ashrrev_i32_e32 v29, 31, v28
	v_lshlrev_b64 v[28:29], 11, v[28:29]
	s_waitcnt lgkmcnt(6)
	v_cvt_pk_bf16_f32 v38, v44, v42
	s_waitcnt lgkmcnt(4)
	v_cvt_pk_bf16_f32 v39, v46, v48
	s_waitcnt lgkmcnt(2)
	v_cvt_pk_bf16_f32 v40, v50, v52
	s_waitcnt lgkmcnt(0)
	v_cvt_pk_bf16_f32 v41, v54, v58
	v_lshl_add_u64 v[28:29], v[56:57], 0, v[28:29]
	global_store_dwordx4 v[28:29], v[38:41], off sc0 sc1
	v_or_b32_e32 v28, s4, v36
	v_ashrrev_i32_e32 v29, 31, v28
	v_lshlrev_b64 v[28:29], 11, v[28:29]
	v_cvt_pk_bf16_f32 v38, v45, v43
	v_cvt_pk_bf16_f32 v39, v47, v49
	v_cvt_pk_bf16_f32 v40, v51, v53
	v_cvt_pk_bf16_f32 v41, v55, v59
	v_lshl_add_u64 v[28:29], v[56:57], 0, v[28:29]
	global_store_dwordx4 v[28:29], v[38:41], off sc0 sc1
	s_waitcnt lgkmcnt(0)
	s_branch .LBB0_14

; #define GAS __attribute__((address_space(1)))
; #define LAS __attribute__((address_space(3)))
; __device__ __forceinline__ unsigned pk2(float lo, float hi) { return pg8::cvt_pk_bf16_c(lo, hi); }
; __device__ __forceinline__ void p0_prologue(const Args& a, LAS unsigned char* lds, int vcu, int G, int tid, int lane, int wave) {
;     ...
;     for (int m = gw; m < T; m += NGW) {
;         f32x4 v[4]; float s2 = 0.f;
; #pragma unroll
;         for (int j = 0; j < 4; ++j) { v[j] = nv[j]; s2 += (v[j].x * v[j].x + v[j].y * v[j].y) + (v[j].z * v[j].z + v[j].w * v[j].w); }
;         if (m + NGW < T) { const GAS f32x4* xr = (const GAS f32x4*)(x + (size_t)(m + NGW) * DM) + lane;
; #pragma unroll
;             for (int j = 0; j < 4; ++j) nv[j] = xr[64 * j]; }
;         const float rstd = 1.0f / sqrtf(wave_sum(s2) * (1.f / DM) + EPS);
; #pragma unroll
;         for (int j = 0; j < 4; ++j) v[j] = v[j] * rstd * gv[j];
;         GAS unsigned long long* o8 = (GAS unsigned long long*)(XN + (size_t)m * DM) + lane;
; #pragma unroll
;         for (int j = 0; j < 4; ++j) o8[64 * j] = (unsigned long long)pk2(v[j].x, v[j].y) | ((unsigned long long)pk2(v[j].z, v[j].w) << 32);
;         float f[8];
; #pragma unroll
;         for (int h = 0; h < 8; ++h) { float acc = 0.f;
; #pragma unroll
;             for (int j = 0; j < 4; ++j) { const f32x4 w = *(const LAS f32x4*)(wf + h * 1024 + 256 * j + 4 * lane); acc += (v[j].x * w.x + v[j].y * w.y) + (v[j].z * w.z + v[j].w * w.w); }
;             f[h] = wave_sum(acc); }
.LBB0_59:
	v_mul_f32_e32 v185, v175, v175
	v_mul_f32_e32 v186, v177, v177
	v_fmac_f32_e32 v185, v174, v174
	v_fmac_f32_e32 v186, v176, v176
	v_add_f32_e32 v185, v185, v186
	v_mul_f32_e32 v186, v171, v171
	v_mul_f32_e32 v187, v173, v173
	v_fmac_f32_e32 v186, v170, v170
	v_fmac_f32_e32 v187, v172, v172
	v_add_f32_e32 v186, v186, v187
	v_add_f32_e32 v185, v186, v185
	v_mul_f32_e32 v186, v167, v167
	v_mul_f32_e32 v187, v169, v169
	v_fmac_f32_e32 v186, v166, v166
	v_fmac_f32_e32 v187, v168, v168
	v_add_f32_e32 v186, v186, v187
	v_add_f32_e32 v185, v186, v185
	v_mul_f32_e32 v186, v163, v163
	v_mul_f32_e32 v187, v165, v165
	v_fmac_f32_e32 v186, v162, v162
	v_fmac_f32_e32 v187, v164, v164
	v_add_f32_e32 v186, v186, v187
	v_add_f32_e32 v185, v186, v185
	ds_bpermute_b32 v186, v1, v185
	s_waitcnt lgkmcnt(0)
	v_add_f32_e32 v185, v185, v186
	ds_bpermute_b32 v186, v189, v185
	s_waitcnt lgkmcnt(0)
	v_add_f32_e32 v185, v185, v186
	ds_bpermute_b32 v186, v190, v185
	s_waitcnt lgkmcnt(0)
	v_add_f32_e32 v185, v185, v186
	ds_bpermute_b32 v186, v191, v185
	s_waitcnt lgkmcnt(0)
	v_add_f32_e32 v185, v185, v186
	ds_bpermute_b32 v186, v192, v185
	s_waitcnt lgkmcnt(0)
	v_add_f32_e32 v185, v185, v186
	ds_bpermute_b32 v186, v193, v185
	s_waitcnt lgkmcnt(0)
	v_add_f32_e32 v185, v185, v186
	v_fmamk_f32 v185, v185, 0x3a800000, v194
	v_mul_f32_e32 v186, 0x4f800000, v185
	v_cmp_gt_f32_e32 vcc, s33, v185
	s_nop 1
	v_cndmask_b32_e32 v185, v185, v186, vcc
	v_sqrt_f32_e32 v186, v185
	s_nop 0
	v_add_u32_e32 v187, -1, v186
	v_add_u32_e32 v198, 1, v186
	v_fma_f32 v199, -v187, v186, v185
	v_fma_f32 v200, -v198, v186, v185
	v_cmp_ge_f32_e64 s[18:19], 0, v199
	s_nop 1
	v_cndmask_b32_e64 v186, v186, v187, s[18:19]
	v_cmp_lt_f32_e64 s[18:19], 0, v200
	s_nop 1
	v_cndmask_b32_e64 v186, v186, v198, s[18:19]
	v_mul_f32_e32 v187, 0x37800000, v186
	v_cndmask_b32_e32 v186, v186, v187, vcc
	v_cmp_class_f32_e32 vcc, v185, v195
	s_nop 1
	v_cndmask_b32_e32 v185, v186, v185, vcc
	v_div_scale_f32 v186, s[18:19], v185, v185, 1.0
	v_rcp_f32_e32 v187, v186
	v_div_scale_f32 v198, vcc, 1.0, v185, 1.0
	v_fma_f32 v199, -v186, v187, 1.0
	v_fmac_f32_e32 v187, v199, v187
	v_mul_f32_e32 v199, v198, v187
	v_fma_f32 v200, -v186, v199, v198
	v_fmac_f32_e32 v199, v200, v187
	v_fma_f32 v186, -v186, v199, v198
	v_div_fmas_f32 v186, v186, v187, v199
	v_div_fixup_f32 v186, v186, v185, 1.0
	v_pk_mul_f32 v[198:199], v[174:175], v[186:187] op_sel_hi:[1,0]
	v_pk_mul_f32 v[174:175], v[176:177], v[186:187] op_sel_hi:[1,0]
	v_pk_mul_f32 v[176:177], v[2:3], v[198:199]
	v_pk_mul_f32 v[174:175], v[4:5], v[174:175]
	v_pk_mul_f32 v[198:199], v[166:167], v[186:187] op_sel_hi:[1,0]
	v_pk_mul_f32 v[200:201], v[170:171], v[186:187] op_sel_hi:[1,0]
	v_pk_mul_f32 v[170:171], v[172:173], v[186:187] op_sel_hi:[1,0]
	v_pk_mul_f32 v[166:167], v[168:169], v[186:187] op_sel_hi:[1,0]
	v_pk_mul_f32 v[168:169], v[10:11], v[198:199]
	v_pk_mul_f32 v[198:199], v[162:163], v[186:187] op_sel_hi:[1,0]
	v_pk_mul_f32 v[162:163], v[164:165], v[186:187] op_sel_hi:[1,0]
	v_mul_f32_e32 v185, v19, v177
	v_mul_f32_e32 v186, v21, v175
	v_pk_mul_f32 v[170:171], v[8:9], v[170:171]
	v_pk_mul_f32 v[172:173], v[6:7], v[200:201]
	v_fmac_f32_e32 v185, v18, v176
	v_fmac_f32_e32 v186, v20, v174
	v_add_f32_e32 v185, v185, v186
	v_mul_f32_e32 v186, v23, v173
	v_mul_f32_e32 v187, v25, v171
	v_fmac_f32_e32 v186, v22, v172
	v_fmac_f32_e32 v187, v24, v170
	v_pk_mul_f32 v[166:167], v[12:13], v[166:167]
	v_add_f32_e32 v185, 0, v185
	v_add_f32_e32 v186, v186, v187
	v_add_f32_e32 v185, v186, v185
	v_mul_f32_e32 v186, v27, v169
	v_mul_f32_e32 v187, v29, v167
	v_fmac_f32_e32 v186, v26, v168
	v_fmac_f32_e32 v187, v28, v166
	v_pk_mul_f32 v[162:163], v[16:17], v[162:163]
	v_pk_mul_f32 v[164:165], v[14:15], v[198:199]
	v_add_f32_e32 v186, v186, v187
	v_add_f32_e32 v185, v186, v185
	v_mul_f32_e32 v186, v31, v165
	v_mul_f32_e32 v187, v33, v163
	v_fmac_f32_e32 v186, v30, v164
	v_fmac_f32_e32 v187, v32, v162
	v_add_f32_e32 v186, v186, v187
	v_mul_f32_e32 v187, v177, v35
	v_mul_f32_e32 v198, v175, v37
	v_fmac_f32_e32 v187, v176, v34
	v_fmac_f32_e32 v198, v174, v36
	v_add_f32_e32 v187, v187, v198
	v_mul_f32_e32 v198, v173, v39
	v_mul_f32_e32 v199, v171, v41
	v_fmac_f32_e32 v198, v172, v38
	v_fmac_f32_e32 v199, v170, v40
	v_add_f32_e32 v187, 0, v187
	v_add_f32_e32 v198, v198, v199
	v_add_f32_e32 v187, v187, v198
	v_mul_f32_e32 v198, v169, v43
	v_mul_f32_e32 v199, v167, v45
	v_fmac_f32_e32 v198, v168, v42
	v_fmac_f32_e32 v199, v166, v44
	v_add_f32_e32 v198, v198, v199
	v_add_f32_e32 v187, v187, v198
	v_mul_f32_e32 v198, v165, v47
	v_mul_f32_e32 v199, v163, v49
	v_fmac_f32_e32 v198, v164, v46
	v_fmac_f32_e32 v199, v162, v48
	v_add_f32_e32 v198, v198, v199
	v_add_f32_e32 v185, v186, v185
	v_add_f32_e32 v187, v187, v198
	ds_bpermute_b32 v186, v1, v185
	ds_bpermute_b32 v198, v1, v187
	v_mul_f32_e32 v202, v175, v53
	v_fmac_f32_e32 v202, v174, v52
	v_mul_f32_e32 v203, v171, v57
	s_waitcnt lgkmcnt(1)
	v_add_f32_e32 v185, v185, v186
	s_waitcnt lgkmcnt(0)
	v_add_f32_e32 v198, v187, v198
	ds_bpermute_b32 v199, v189, v185
	ds_bpermute_b32 v200, v189, v198
	v_fmac_f32_e32 v203, v170, v56
	v_mul_f32_e32 v204, v175, v69
	v_fmac_f32_e32 v204, v174, v68
	s_waitcnt lgkmcnt(1)
	v_add_f32_e32 v185, v185, v199
	s_waitcnt lgkmcnt(0)
	v_add_f32_e32 v198, v198, v200
	ds_bpermute_b32 v199, v190, v185
	ds_bpermute_b32 v200, v190, v198
	v_mul_f32_e32 v205, v171, v73
	v_fmac_f32_e32 v205, v170, v72
	v_mul_f32_e32 v206, v175, v85
	s_waitcnt lgkmcnt(1)
	v_add_f32_e32 v185, v185, v199
	s_waitcnt lgkmcnt(0)
	v_add_f32_e32 v198, v198, v200
	ds_bpermute_b32 v199, v191, v185
	ds_bpermute_b32 v200, v191, v198
	v_fmac_f32_e32 v206, v174, v84
	v_mul_f32_e32 v207, v171, v89
	v_fmac_f32_e32 v207, v170, v88
	s_waitcnt lgkmcnt(1)
; #define GAS __attribute__((address_space(1)))
; #define LAS __attribute__((address_space(3)))
; __device__ __forceinline__ unsigned pk2(float lo, float hi) { return pg8::cvt_pk_bf16_c(lo, hi); }
; __device__ __forceinline__ void p0_prologue(const Args& a, LAS unsigned char* lds, int vcu, int G, int tid, int lane, int wave) {
;     ...
;         for (int j = 0; j < 4; ++j) v[j] = v[j] * rstd * gv[j];
;         GAS unsigned long long* o8 = (GAS unsigned long long*)(XN + (size_t)m * DM) + lane;
; #pragma unroll
;         for (int j = 0; j < 4; ++j) o8[64 * j] = (unsigned long long)pk2(v[j].x, v[j].y) | ((unsigned long long)pk2(v[j].z, v[j].w) << 32);
;         float f[8];
; #pragma unroll
;         for (int h = 0; h < 8; ++h) { float acc = 0.f;
; #pragma unroll
;             for (int j = 0; j < 4; ++j) { const f32x4 w = *(const LAS f32x4*)(wf + h * 1024 + 256 * j + 4 * lane); acc += (v[j].x * w.x + v[j].y * w.y) + (v[j].z * w.z + v[j].w * w.w); }
;             f[h] = wave_sum(acc); }
	v_add_f32_e32 v185, v185, v199
	s_waitcnt lgkmcnt(0)
	v_add_f32_e32 v200, v198, v200
	ds_bpermute_b32 v199, v192, v185
	ds_bpermute_b32 v201, v192, v200
	v_mul_f32_e32 v208, v175, v101
	v_fmac_f32_e32 v208, v174, v100
	v_mul_f32_e32 v209, v171, v105
	s_waitcnt lgkmcnt(1)
	v_add_f32_e32 v185, v185, v199
	s_waitcnt lgkmcnt(0)
	v_add_f32_e32 v199, v200, v201
	v_mul_f32_e32 v201, v177, v51
	v_fmac_f32_e32 v201, v176, v50
	v_add_f32_e32 v201, v201, v202
	v_mul_f32_e32 v202, v173, v55
	v_fmac_f32_e32 v202, v172, v54
	v_add_f32_e32 v201, 0, v201
	v_add_f32_e32 v202, v202, v203
	v_add_f32_e32 v201, v201, v202
	v_mul_f32_e32 v202, v169, v59
	v_mul_f32_e32 v203, v167, v61
	v_fmac_f32_e32 v202, v168, v58
	v_fmac_f32_e32 v203, v166, v60
	v_add_f32_e32 v202, v202, v203
	v_add_f32_e32 v201, v201, v202
	v_mul_f32_e32 v202, v165, v63
	v_mul_f32_e32 v203, v163, v65
	v_fmac_f32_e32 v202, v164, v62
	v_fmac_f32_e32 v203, v162, v64
	v_add_f32_e32 v202, v202, v203
	v_mul_f32_e32 v203, v177, v67
	v_fmac_f32_e32 v203, v176, v66
	v_add_f32_e32 v203, v203, v204
	v_mul_f32_e32 v204, v173, v71
	v_fmac_f32_e32 v204, v172, v70
	v_add_f32_e32 v203, 0, v203
	v_add_f32_e32 v204, v204, v205
	v_add_f32_e32 v203, v203, v204
	v_mul_f32_e32 v204, v169, v75
	v_mul_f32_e32 v205, v167, v77
	v_fmac_f32_e32 v204, v168, v74
	v_fmac_f32_e32 v205, v166, v76
	v_add_f32_e32 v204, v204, v205
	v_add_f32_e32 v203, v203, v204
	v_mul_f32_e32 v204, v165, v79
	v_mul_f32_e32 v205, v163, v81
	v_fmac_f32_e32 v204, v164, v78
	v_fmac_f32_e32 v205, v162, v80
	v_add_f32_e32 v204, v204, v205
	v_mul_f32_e32 v205, v177, v83
	v_fmac_f32_e32 v205, v176, v82
	v_add_f32_e32 v205, v205, v206
	v_mul_f32_e32 v206, v173, v87
	v_fmac_f32_e32 v206, v172, v86
	v_add_f32_e32 v205, 0, v205
	v_add_f32_e32 v206, v206, v207
	v_add_f32_e32 v205, v205, v206
	v_mul_f32_e32 v206, v169, v91
	v_mul_f32_e32 v207, v167, v93
	v_fmac_f32_e32 v206, v168, v90
	v_fmac_f32_e32 v207, v166, v92
	v_add_f32_e32 v206, v206, v207
	v_add_f32_e32 v205, v205, v206
	v_mul_f32_e32 v206, v165, v95
	v_mul_f32_e32 v207, v163, v97
	v_fmac_f32_e32 v206, v164, v94
	v_fmac_f32_e32 v207, v162, v96
	v_add_f32_e32 v206, v206, v207
	v_mul_f32_e32 v207, v177, v99
	v_fmac_f32_e32 v207, v176, v98
	v_add_f32_e32 v207, v207, v208
	v_mul_f32_e32 v208, v173, v103
	v_fmac_f32_e32 v208, v172, v102
	v_fmac_f32_e32 v209, v170, v104
	v_add_f32_e32 v207, 0, v207
	v_add_f32_e32 v208, v208, v209
	v_add_f32_e32 v207, v207, v208
	v_mul_f32_e32 v208, v169, v107
	v_mul_f32_e32 v209, v167, v109
	v_fmac_f32_e32 v208, v168, v106
	v_fmac_f32_e32 v209, v166, v108
	v_add_f32_e32 v208, v208, v209
	v_add_f32_e32 v207, v207, v208
	v_mul_f32_e32 v208, v165, v111
	v_mul_f32_e32 v209, v163, v113
	v_fmac_f32_e32 v208, v164, v110
	v_fmac_f32_e32 v209, v162, v112
	v_add_f32_e32 v208, v208, v209
	v_mul_f32_e32 v209, v177, v115
	v_mul_f32_e32 v210, v175, v117
	v_fmac_f32_e32 v209, v176, v114
	v_fmac_f32_e32 v210, v174, v116
	v_add_f32_e32 v209, v209, v210
	v_mul_f32_e32 v210, v173, v119
	v_mul_f32_e32 v211, v171, v121
	v_fmac_f32_e32 v210, v172, v118
	v_fmac_f32_e32 v211, v170, v120
	v_cvt_pk_bf16_f32 v186, v176, v177
	v_cvt_pk_bf16_f32 v187, v174, v175
	v_add_f32_e32 v209, 0, v209
	v_add_f32_e32 v210, v210, v211
	global_store_dwordx2 v[180:181], v[186:187], off sc0 sc1
	v_cvt_pk_bf16_f32 v186, v172, v173
	v_cvt_pk_bf16_f32 v187, v170, v171
	v_add_f32_e32 v209, v209, v210
	v_mul_f32_e32 v210, v169, v123
	v_mul_f32_e32 v211, v167, v125
	v_mul_f32_e32 v177, v177, v131
	v_mul_f32_e32 v175, v175, v133
	global_store_dwordx2 v[180:181], v[186:187], off offset:512 sc0 sc1
	v_cvt_pk_bf16_f32 v186, v168, v169
	v_cvt_pk_bf16_f32 v187, v166, v167
	v_fmac_f32_e32 v210, v168, v122
	v_fmac_f32_e32 v211, v166, v124
	v_fmac_f32_e32 v177, v176, v130
	v_fmac_f32_e32 v175, v174, v132
	v_mul_f32_e32 v173, v173, v135
	v_mul_f32_e32 v171, v171, v137
	v_mul_f32_e32 v169, v169, v139
	v_mul_f32_e32 v167, v167, v141
	v_add_f32_e32 v210, v210, v211
	v_add_f32_e32 v174, v177, v175
	v_fmac_f32_e32 v173, v172, v134
	v_fmac_f32_e32 v171, v170, v136
	v_fmac_f32_e32 v169, v168, v138
	v_fmac_f32_e32 v167, v166, v140
	v_add_f32_e32 v209, v209, v210
	v_mul_f32_e32 v210, v165, v127
	v_mul_f32_e32 v211, v163, v129
	v_add_f32_e32 v174, 0, v174
	v_add_f32_e32 v170, v173, v171
	v_add_f32_e32 v166, v169, v167
	v_mul_f32_e32 v167, v165, v143
	v_mul_f32_e32 v168, v163, v145
	v_fmac_f32_e32 v210, v164, v126
	v_fmac_f32_e32 v211, v162, v128
	v_add_f32_e32 v170, v174, v170
	v_fmac_f32_e32 v167, v164, v142
	v_fmac_f32_e32 v168, v162, v144
	v_add_f32_e32 v210, v210, v211
	v_add_f32_e32 v166, v170, v166
	v_add_f32_e32 v167, v167, v168
	v_add_f32_e32 v201, v201, v202
	v_add_f32_e32 v203, v203, v204
	v_add_f32_e32 v205, v205, v206
	v_add_f32_e32 v207, v207, v208
	v_add_f32_e32 v209, v209, v210
	v_add_f32_e32 v166, v166, v167
	ds_bpermute_b32 v202, v1, v201
	ds_bpermute_b32 v204, v1, v203
	ds_bpermute_b32 v206, v1, v205
	ds_bpermute_b32 v208, v1, v207
	ds_bpermute_b32 v210, v1, v209
	ds_bpermute_b32 v167, v1, v166
	s_waitcnt lgkmcnt(5)
	v_add_f32_e32 v201, v201, v202
	s_waitcnt lgkmcnt(4)
	v_add_f32_e32 v203, v203, v204
	s_waitcnt lgkmcnt(3)
	v_add_f32_e32 v205, v205, v206
	s_waitcnt lgkmcnt(2)
	v_add_f32_e32 v168, v207, v208
	s_waitcnt lgkmcnt(1)
	v_add_f32_e32 v170, v209, v210
	s_waitcnt lgkmcnt(0)
	v_add_f32_e32 v166, v166, v167
	ds_bpermute_b32 v202, v189, v201
	ds_bpermute_b32 v204, v189, v203
	ds_bpermute_b32 v206, v189, v205
	ds_bpermute_b32 v169, v189, v168
	ds_bpermute_b32 v171, v189, v170
	ds_bpermute_b32 v167, v189, v166
	s_waitcnt lgkmcnt(5)
	v_add_f32_e32 v201, v201, v202
	s_waitcnt lgkmcnt(4)
	v_add_f32_e32 v203, v203, v204
	s_waitcnt lgkmcnt(3)
; #define LAS __attribute__((address_space(3)))
; __device__ __forceinline__ unsigned pk2(float lo, float hi) { return pg8::cvt_pk_bf16_c(lo, hi); }
; __device__ __forceinline__ void p0_prologue(const Args& a, LAS unsigned char* lds, int vcu, int G, int tid, int lane, int wave) {
;     ...
;         for (int j = 0; j < 4; ++j) o8[64 * j] = (unsigned long long)pk2(v[j].x, v[j].y) | ((unsigned long long)pk2(v[j].z, v[j].w) << 32);
;         float f[8];
; #pragma unroll
;         for (int h = 0; h < 8; ++h) { float acc = 0.f;
; #pragma unroll
;             for (int j = 0; j < 4; ++j) { const f32x4 w = *(const LAS f32x4*)(wf + h * 1024 + 256 * j + 4 * lane); acc += (v[j].x * w.x + v[j].y * w.y) + (v[j].z * w.z + v[j].w * w.w); }
;             f[h] = wave_sum(acc); }
;         float fz = f[0];
; #pragma unroll
;         for (int h = 1; h < 8; ++h) fz = (lane == h) ? f[h] : fz;
	v_add_f32_e32 v205, v205, v206
	s_waitcnt lgkmcnt(2)
	v_add_f32_e32 v168, v168, v169
	s_waitcnt lgkmcnt(1)
	v_add_f32_e32 v170, v170, v171
	s_waitcnt lgkmcnt(0)
	v_add_f32_e32 v166, v166, v167
	ds_bpermute_b32 v202, v190, v201
	ds_bpermute_b32 v204, v190, v203
	ds_bpermute_b32 v206, v190, v205
	ds_bpermute_b32 v169, v190, v168
	ds_bpermute_b32 v171, v190, v170
	ds_bpermute_b32 v167, v190, v166
	s_waitcnt lgkmcnt(5)
	v_add_f32_e32 v201, v201, v202
	s_waitcnt lgkmcnt(4)
	v_add_f32_e32 v203, v203, v204
	s_waitcnt lgkmcnt(3)
	v_add_f32_e32 v205, v205, v206
	s_waitcnt lgkmcnt(2)
	v_add_f32_e32 v168, v168, v169
	s_waitcnt lgkmcnt(1)
	v_add_f32_e32 v170, v170, v171
	s_waitcnt lgkmcnt(0)
	v_add_f32_e32 v166, v166, v167
	ds_bpermute_b32 v202, v191, v201
	ds_bpermute_b32 v204, v191, v203
	ds_bpermute_b32 v206, v191, v205
	ds_bpermute_b32 v169, v191, v168
	ds_bpermute_b32 v171, v191, v170
	ds_bpermute_b32 v167, v191, v166
	s_waitcnt lgkmcnt(5)
	v_add_f32_e32 v201, v201, v202
	s_waitcnt lgkmcnt(4)
	v_add_f32_e32 v203, v203, v204
	s_waitcnt lgkmcnt(3)
	v_add_f32_e32 v205, v205, v206
	s_waitcnt lgkmcnt(2)
	v_add_f32_e32 v168, v168, v169
	s_waitcnt lgkmcnt(1)
	v_add_f32_e32 v170, v170, v171
	s_waitcnt lgkmcnt(0)
	v_add_f32_e32 v172, v166, v167
	ds_bpermute_b32 v202, v192, v201
	ds_bpermute_b32 v204, v192, v203
	ds_bpermute_b32 v206, v192, v205
	ds_bpermute_b32 v169, v192, v168
	ds_bpermute_b32 v171, v192, v170
	ds_bpermute_b32 v173, v192, v172
	s_waitcnt lgkmcnt(5)
	v_add_f32_e32 v201, v201, v202
	s_waitcnt lgkmcnt(4)
	v_add_f32_e32 v203, v203, v204
	s_waitcnt lgkmcnt(3)
	v_add_f32_e32 v205, v205, v206
	s_waitcnt lgkmcnt(2)
	v_add_f32_e32 v166, v168, v169
	s_waitcnt lgkmcnt(1)
	v_add_f32_e32 v168, v170, v171
	s_waitcnt lgkmcnt(0)
	v_add_f32_e32 v170, v172, v173
	ds_bpermute_b32 v198, v193, v185
	ds_bpermute_b32 v200, v193, v199
	ds_bpermute_b32 v202, v193, v201
	ds_bpermute_b32 v204, v193, v203
	ds_bpermute_b32 v206, v193, v205
	ds_bpermute_b32 v167, v193, v166
	ds_bpermute_b32 v169, v193, v168
	ds_bpermute_b32 v171, v193, v170
	v_cvt_pk_bf16_f32 v164, v164, v165
	v_cvt_pk_bf16_f32 v165, v162, v163
	global_store_dwordx2 v[180:181], v[186:187], off offset:1024 sc0 sc1
	global_store_dwordx2 v[180:181], v[164:165], off offset:1536 sc0 sc1
	s_and_saveexec_b64 s[18:19], s[0:1]
	s_cbranch_execz .LBB0_56
; __device__ __forceinline__ void p0_prologue(const Args& a, LAS unsigned char* lds, int vcu, int G, int tid, int lane, int wave) {
;     ...
;         float fz = f[0];
; #pragma unroll
;         for (int h = 1; h < 8; ++h) fz = (lane == h) ? f[h] : fz;
;         if (lane < 8) { const float z = fz + b_f[lane]; const float ls = fminf(z, 0.f) - log1pf(expf(-fabsf(z)));
;             const int b = m >> 12, s = m & 4095; logf_[((size_t)(b * NH + lane) << 12) + s] = ls; }
	global_load_dword v164, v[178:179], off
	s_waitcnt lgkmcnt(0)
	v_add_f32_e32 v165, v170, v171
	v_add_f32_e32 v162, v199, v200
	v_add_f32_e32 v170, v185, v198
	v_add_f32_e32 v163, v201, v202
	v_cndmask_b32_e64 v170, v170, v162, s[14:15]
	v_add_f32_e32 v168, v168, v169
	v_add_f32_e32 v169, v203, v204
	v_cndmask_b32_e64 v170, v170, v163, s[12:13]
	v_add_f32_e32 v166, v166, v167
	v_add_f32_e32 v167, v205, v206
	v_cndmask_b32_e64 v169, v170, v169, s[10:11]
	v_cndmask_b32_e64 v167, v169, v167, s[8:9]
	v_cndmask_b32_e64 v166, v167, v166, s[6:7]
	v_cndmask_b32_e64 v166, v166, v168, s[4:5]
	v_cndmask_b32_e64 v165, v166, v165, s[16:17]
	s_and_b32 s38, s62, 0xfff
	s_ashr_i32 s62, s62, 9
	v_and_or_b32 v162, s62, -8, v188
	v_ashrrev_i32_e32 v163, 31, v162
	v_lshlrev_b64 v[162:163], 14, v[162:163]
	s_lshl_b32 s38, s38, 2
	v_lshl_add_u64 v[162:163], s[20:21], 0, v[162:163]
	v_lshl_add_u64 v[162:163], v[162:163], 0, s[38:39]
	s_waitcnt vmcnt(0)
	v_add_f32_e32 v164, v165, v164
	v_mul_f32_e64 v165, |v164|, s35
	v_fma_f32 v166, |v164|, s35, -v165
	v_rndne_f32_e32 v167, v165
	v_fma_f32 v166, |v164|, s54, v166
	v_sub_f32_e32 v165, v165, v167
	v_add_f32_e32 v165, v165, v166
	v_cvt_i32_f32_e32 v167, v167
	v_exp_f32_e32 v165, v165
	v_cmp_ngt_f32_e64 vcc, |v164|, s55
	v_min_f32_e32 v186, 0, v164
	v_ldexp_f32 v165, v165, v167
	v_cndmask_b32_e32 v165, 0, v165, vcc
	v_cmp_nlt_f32_e64 vcc, |v164|, s56
	s_nop 1
	v_cndmask_b32_e32 v187, v197, v165, vcc
	v_add_f32_e32 v166, 1.0, v187
	v_add_f32_e32 v167, -1.0, v166
	v_frexp_mant_f32_e32 v168, v166
	v_cvt_f64_f32_e32 v[164:165], v166
	v_sub_f32_e32 v169, v167, v166
	v_frexp_exp_i32_f64_e32 v164, v[164:165]
	v_cmp_gt_f32_e32 vcc, s58, v168
	v_sub_f32_e32 v167, v187, v167
	v_add_f32_e32 v165, 1.0, v169
	v_subbrev_co_u32_e32 v164, vcc, 0, v164, vcc
	v_add_f32_e32 v165, v167, v165
	v_sub_u32_e32 v167, 0, v164
	v_ldexp_f32 v166, v166, v167
	v_add_f32_e32 v168, -1.0, v166
	v_add_f32_e32 v169, 1.0, v166
	v_ldexp_f32 v165, v165, v167
	v_add_f32_e32 v167, 1.0, v168
	v_add_f32_e32 v170, -1.0, v169
	v_sub_f32_e32 v167, v166, v167
	v_sub_f32_e32 v166, v166, v170
	v_add_f32_e32 v170, v165, v167
	v_add_f32_e32 v165, v165, v166
	v_add_f32_e32 v172, v169, v165
	v_rcp_f32_e32 v173, v172
	v_add_f32_e32 v167, v168, v170
	v_sub_f32_e32 v168, v168, v167
	v_sub_f32_e32 v166, v169, v172
	v_mul_f32_e32 v175, v167, v173
	v_add_f32_e32 v174, v170, v168
	v_mul_f32_e32 v168, v172, v175
	v_add_f32_e32 v165, v165, v166
	v_fma_f32 v170, v175, v172, -v168
	v_fmac_f32_e32 v170, v175, v165
	v_add_f32_e32 v166, v168, v170
	v_sub_f32_e32 v169, v167, v166
	v_mov_b32_e32 v171, v166
	v_pk_add_f32 v[166:167], v[166:167], v[168:169] neg_lo:[0,1] neg_hi:[0,1]
	v_cvt_f32_i32_e32 v164, v164
	v_pk_add_f32 v[166:167], v[166:167], v[170:171] neg_lo:[0,1] neg_hi:[0,1]
	v_cmp_neq_f32_e32 vcc, s57, v187
	v_add_f32_e32 v167, v174, v167
	v_add_f32_e32 v166, v166, v167
	v_add_f32_e32 v167, v169, v166
	v_mul_f32_e32 v171, v173, v167
	v_mul_f32_e32 v168, v172, v171
	v_sub_f32_e32 v169, v169, v167
	v_add_f32_e32 v176, v175, v171
	v_fma_f32 v170, v171, v172, -v168
	v_add_f32_e32 v174, v166, v169
	v_sub_f32_e32 v166, v176, v175
	v_fmac_f32_e32 v170, v171, v165
	v_sub_f32_e32 v165, v171, v166
	v_add_f32_e32 v166, v168, v170
	v_sub_f32_e32 v169, v167, v166
	v_mov_b32_e32 v171, v166
	v_pk_add_f32 v[166:167], v[166:167], v[168:169] neg_lo:[0,1] neg_hi:[0,1]
	s_nop 0
	v_pk_add_f32 v[166:167], v[166:167], v[170:171] neg_lo:[0,1] neg_hi:[0,1]
	s_nop 0
	v_add_f32_e32 v167, v174, v167
	v_add_f32_e32 v166, v166, v167
	v_add_f32_e32 v166, v169, v166
	v_mul_f32_e32 v166, v173, v166
	v_add_f32_e32 v165, v165, v166
	v_add_f32_e32 v166, v176, v165
	v_mul_f32_e32 v168, v166, v166
	v_sub_f32_e32 v169, v166, v176
	v_fmamk_f32 v170, v168, 0x3e9b6dac, v196
	v_sub_f32_e32 v169, v165, v169
	v_mul_f32_e32 v165, v166, v168
	v_fmaak_f32 v185, v168, v170, 0x3f2aaada
	v_ldexp_f32 v171, v169, 1
	v_pk_mul_f32 v[168:169], v[164:165], v[184:185]
	v_ldexp_f32 v167, v166, 1
	v_fma_f32 v166, v164, s59, -v168
	v_fmac_f32_e32 v166, 0xb102e308, v164
	v_pk_add_f32 v[164:165], v[168:169], v[166:167]
	v_mov_b32_e32 v170, v168
	v_sub_f32_e32 v174, v165, v167
	v_pk_add_f32 v[172:173], v[164:165], v[168:169] neg_lo:[0,1] neg_hi:[0,1]
	v_sub_f32_e32 v168, v169, v174
	v_add_f32_e32 v171, v171, v168
	v_pk_add_f32 v[168:169], v[164:165], v[170:171]
	v_mov_b32_e32 v167, v164
	v_mov_b32_e32 v173, v169
	v_pk_add_f32 v[176:177], v[166:167], v[172:173] neg_lo:[0,1] neg_hi:[0,1]
	v_pk_add_f32 v[166:167], v[166:167], v[172:173]
	v_mov_b32_e32 v175, v164
	v_pk_add_f32 v[172:173], v[166:167], v[164:165] op_sel:[1,0] op_sel_hi:[0,1] neg_lo:[0,1] neg_hi:[0,1]
	v_mov_b32_e32 v174, v171
	v_mov_b32_e32 v170, v169
	v_mov_b32_e32 v171, v167
	v_pk_mov_b32 v[164:165], v[164:165], v[172:173] op_sel:[1,0]
	v_pk_add_f32 v[168:169], v[168:169], v[172:173] op_sel_hi:[1,0] neg_lo:[0,1] neg_hi:[0,1]
	v_pk_add_f32 v[164:165], v[170:171], v[164:165] neg_lo:[0,1] neg_hi:[0,1]
	v_mov_b32_e32 v168, v176
	v_pk_add_f32 v[164:165], v[174:175], v[164:165] neg_lo:[0,1] neg_hi:[0,1]
	v_mov_b32_e32 v177, v167
	v_pk_add_f32 v[168:169], v[168:169], v[164:165]
	s_nop 0
	v_pk_add_f32 v[170:171], v[168:169], v[168:169] op_sel:[0,1] op_sel_hi:[1,0]
	s_nop 0
	v_pk_add_f32 v[166:167], v[166:167], v[170:171] op_sel:[1,0] op_sel_hi:[0,1]
	v_mov_b32_e32 v169, v166
	v_mov_b32_e32 v165, v170
	v_pk_add_f32 v[170:171], v[168:169], v[176:177] neg_lo:[0,1] neg_hi:[0,1]
	s_nop 0
	v_sub_f32_e32 v167, v168, v170
	v_pk_add_f32 v[164:165], v[164:165], v[170:171] neg_lo:[0,1] neg_hi:[0,1]
	v_sub_f32_e32 v167, v176, v167
	v_add_f32_e32 v164, v164, v167
	v_add_f32_e32 v164, v164, v165
	v_add_f32_e32 v164, v166, v164
	v_cndmask_b32_e32 v164, v197, v164, vcc
	v_cmp_lt_f32_e64 vcc, |v187|, s63
	s_nop 1
	v_cndmask_b32_e32 v164, v164, v187, vcc
	v_sub_f32_e32 v164, v186, v164
	global_store_dword v[162:163], v164, off
	s_branch .LBB0_56

; #define PH_IDS() int tid = threadIdx.x; asm volatile("" : "+v"(tid)); const int lane = tid & 63
; __global__ void __launch_bounds__(NWAVES * 64, 2) fwd_mega(Args args) {
;     ...
;     if (IN(1)) {
;         { PH_IDS(); for (int bh = vcu; bh < BATCH * NH; bh += G) cumsum_bh(logf_, cc, bh, lds, tid, lane, wave); }
;         pg8::Gemm g{XN, (const bf16*)(ws + WS_W1), T, NP1, DM}; pg8::StaticOrder S; S.init(T, NP1, G, bx);
;         pg8::EpiP1 E{AO, VA, ZA, KB, VB, ZB};
;         pg8::gemm_phase<pg8::EpiP1, pg8::StaticOrder, true, true>(lds, g, S, E);
.LBB0_93:
	s_andn2_b64 vcc, exec, s[6:7]
	s_cbranch_vccnz .LBB0_162
	s_bfe_u32 s5, s2, 0x20003
	s_cmp_eq_u32 s5, 0
	s_cbranch_scc1 .Lp1_nostag
.Lp1_stag:
	s_sleep 100
	s_sub_u32 s5, s5, 1
	s_cmp_lg_u32 s5, 0
	s_cbranch_scc1 .Lp1_stag
